# plus: attention wave-done flags in one LDS round trip; retention head norm reductions issued four at a time, one load drain per chunk, stores left in flight
# speedup vs baseline: 1.0147x; 1.0029x over previous
.LBB0_1054:
	s_cmp_ge_u32 s57, s20
	s_cselect_b64 s[36:37], -1, 0
	s_and_b64 vcc, exec, s[36:37]
	s_waitcnt lgkmcnt(0)
	s_barrier
	s_cbranch_vccnz .LBB0_1056
	v_readlane_b32 s21, v254, 38
	s_nop 1
	v_mov_b32_e32 v1, s21
	ds_read_b32 v42, v1 offset:4
	ds_read_b32 v1, v1
	s_waitcnt lgkmcnt(0)
	v_and_b32_e32 v1, v1, v42
	v_and_b32_e32 v1, 0x1010101, v1
	v_xor_b32_e32 v1, 0x1010101, v1
	v_cmp_ne_u32_e64 s[36:37], 0, v1

.LBB0_1084:
	v_readlane_b32 s21, v253, 34
	v_cndmask_b32_e64 v1, 0, 1, s[34:35]
	s_nop 0
	v_mov_b32_e32 v54, s21
	v_subrev_u32_e32 v54, 0x20140, v54
	v_lshrrev_b32_e32 v54, 2, v54
	v_add_u32_e32 v54, 0x201a0, v54
	ds_write_b8 v54, v1

.LBB0_1086:
	s_cmp_eq_u32 s56, 0
	s_cselect_b64 s[50:51], -1, 0
	s_or_b64 s[38:39], s[50:51], s[38:39]
	s_mov_b64 s[36:37], -1
	s_and_b64 vcc, exec, s[38:39]
	s_cbranch_vccnz .LBB0_1052
	s_cmp_gt_u32 s57, s20
	s_cselect_b64 s[36:37], -1, 0
	s_cmp_le_u32 s57, s20
	s_waitcnt lgkmcnt(0)
	s_barrier
	s_cbranch_scc0 .LBB0_1089
	v_readlane_b32 s21, v254, 38
	s_nop 1
	v_mov_b32_e32 v1, s21
	ds_read_b32 v54, v1 offset:4
	ds_read_b32 v1, v1
	s_waitcnt lgkmcnt(0)
	v_and_b32_e32 v1, v1, v54
	v_and_b32_e32 v1, 0x1010101, v1
	v_xor_b32_e32 v1, 0x1010101, v1
	v_cmp_ne_u32_e64 s[36:37], 0, v1

.LBB0_1117:
	v_readlane_b32 s21, v253, 34
	v_cndmask_b32_e64 v1, 0, 1, s[34:35]
	s_nop 0
	v_mov_b32_e32 v42, s21
	v_subrev_u32_e32 v42, 0x20140, v42
	v_lshrrev_b32_e32 v42, 2, v42
	v_add_u32_e32 v42, 0x201a0, v42
	ds_write_b8 v42, v1

; __device__ __forceinline__ float fast_exp2(float x) { return __builtin_amdgcn_exp2f(x); }
; #define RT_CHUNK(c, rb, vl) do { if (stream == 0) { if ((c) == 0) { rb = ROW_M; vl = NMETA; } else { rb = b * T + 64 * ((c) - 1); vl = 64; } } \
;         else if (stream == 1) { rb = ROW_S + b * ST; vl = ST; } else { rb = ROW_M; vl = NMETA; } } while (0)
; __device__ __forceinline__ void ret_unit(const Frame& F, int layer, int uid) {
;     ...
;     for (int c = 0; c < nch; ++c) {
;         int rowbase, valid; RT_CHUNK(c, rowbase, valid);
;         const bool write_out = !(stream == 0 && c == 0);
;         const float dc = fast_exp2((float)valid * lg2);
;         __syncthreads();
.LBB0_1381:
	s_cmp_eq_u32 s93, 0
	s_cselect_b64 s[38:39], -1, 0
	s_and_b64 s[42:43], s[38:39], exec
	s_cselect_b32 s53, 16, 64
	s_and_b64 s[42:43], exec, s[94:95]
	s_cselect_b32 s67, s76, s53
	s_add_i32 s53, s93, 1
	s_cmp_ge_u32 s53, s49
	s_waitcnt lgkmcnt(0)
	s_barrier
	s_cselect_b32 s100, 1, 0
	s_cmp_lt_u32 s93, 2
	s_cbranch_scc1 .Lret_top_full
	s_waitcnt vmcnt(8)
	s_branch .Lret_top_go

; #define LAS __attribute__((address_space(3)))
; __device__ __forceinline__ void ret_unit(const Frame& F, int layer, int uid) {
;     ...
;         __syncthreads();
; #pragma unroll
;         for (int i = 0; i < 2; ++i) { *(LAS v4u*)(F.lds + RT_Q + (lrow + 32 * i) * RT_QS + lch * 16) = qreg[i]; *(LAS v4u*)(F.lds + RT_K + (lrow + 32 * i) * RT_QS + lch * 16) = kreg[i]; }
; #pragma unroll
;         for (int i = 0; i < 4; ++i) *(LAS v4u*)(F.lds + RT_V + (vrow + 16 * i) * RT_VS + vch * 16) = vreg[i];
;         __syncthreads();
;         if (c + 1 < nch) RT_LOAD(c + 1);
.Lret_top_go:
	s_cmp_lg_u32 s100, 0
	ds_write_b128 v193, v[4:7]
	ds_write_b128 v193, v[8:11] offset:17408
	ds_write_b128 v193, v[12:15] offset:8704
	ds_write_b128 v193, v[16:19] offset:26112
	ds_write_b128 v210, v[20:23] offset:34816
	ds_write_b128 v210, v[24:27] offset:43264
	ds_write_b128 v210, v[28:31] offset:51712
	ds_write_b128 v210, v[32:35] offset:60160
	s_waitcnt lgkmcnt(0)
	s_barrier
	s_cbranch_scc1 .LBB0_1395
	v_mov_b32_e32 v12, v0
	v_mov_b32_e32 v13, v0
	s_and_b64 s[42:43], exec, s[94:95]
	v_mov_b32_e32 v14, v0
	v_mov_b32_e32 v15, v0
	v_mov_b64_e32 v[4:5], v[12:13]
	v_mov_b64_e32 v[8:9], v[12:13]
	s_cselect_b32 s85, s97, s54
	v_mov_b64_e32 v[6:7], v[14:15]
	v_mov_b64_e32 v[10:11], v[14:15]
	s_and_saveexec_b64 s[42:43], s[24:25]
	s_cbranch_execz .LBB0_1384
	v_add_u32_e32 v2, s85, v149
	v_ashrrev_i32_e32 v3, 31, v2
	v_lshlrev_b64 v[2:3], 10, v[2:3]
	s_mov_b64 s[90:91], s[46:47]
	v_lshl_or_b32 v2, v155, 1, v2
	s_nop 0
	v_lshl_add_u64 v[4:5], s[90:91], 0, v[2:3]
	v_add_co_u32_e32 v4, vcc, 0x265c0000, v4
	s_mov_b64 s[90:91], s[46:47]
	s_nop 0
	v_addc_co_u32_e32 v5, vcc, 0, v5, vcc
	global_load_dwordx4 v[4:7], v[4:5], off
	s_nop 0
	v_lshl_add_u64 v[2:3], s[90:91], 0, v[2:3]
	v_add_co_u32_e32 v2, vcc, 0x2a640000, v2
	s_nop 1
	v_addc_co_u32_e32 v3, vcc, 0, v3, vcc
	global_load_dwordx4 v[8:11], v[2:3], off

; __device__ __forceinline__ unsigned cvt_pk_bf16(float lo, float hi) { unsigned r; asm volatile("v_cvt_pk_bf16_f32 %0, %1, %2" : "=v"(r) : "v"(lo), "v"(hi)); return r; }
; #define LAS __attribute__((address_space(3)))
; __device__ __forceinline__ void ret_unit(const Frame& F, int layer, int uid) {
;     ...
;             *(LAS v2u*)(F.lds + RT_A + (16 * nt + l15) * RT_AS + (16 * mt + 4 * g) * 2) = (v2u){pg8::cvt_pk_bf16(a4[0], a4[1]), pg8::cvt_pk_bf16(a4[2], a4[3])}; }
;         __syncthreads();
;         f32x4 accO[4][2];
; #pragma unroll
;         for (int m = 0; m < 4; ++m)
; #pragma unroll
;             for (int n = 0; n < 2; ++n) accO[m][n] = (f32x4){0.f, 0.f, 0.f, 0.f};
; #pragma unroll
;         for (int ks = 0; ks < 4; ++ks) {
;             bf16x8 Sf[2];
; #pragma unroll
;             for (int n = 0; n < 2; ++n) Sf[n] = __builtin_bit_cast(bf16x8, (v4u){pg8::cvt_pk_bf16(accS[2 * ks][n][0], accS[2 * ks][n][1]), pg8::cvt_pk_bf16(accS[2 * ks][n][2], accS[2 * ks][n][3]),
;                                                                                pg8::cvt_pk_bf16(accS[2 * ks + 1][n][0], accS[2 * ks + 1][n][1]), pg8::cvt_pk_bf16(accS[2 * ks + 1][n][2], accS[2 * ks + 1][n][3])});
; #pragma unroll
;             for (int m = 0; m < 4; ++m) { const v2u lo = *(const LAS v2u*)(Ql + (16 * m + l15) * RT_QS + (32 * ks + 4 * g) * 2), hi = *(const LAS v2u*)(Ql + (16 * m + l15) * RT_QS + (32 * ks + 16 + 4 * g) * 2);
;                 const bf16x8 A = __builtin_bit_cast(bf16x8, (v4u){lo.x, lo.y, hi.x, hi.y});
; #pragma unroll
;                 for (int n = 0; n < 2; ++n) accO[m][n] = MFMA16(A, Sf[n], accO[m][n]); }
;         }
;         bf16x8 Bv[2][2];
; #pragma unroll
;         for (int k2 = 0; k2 < 2; ++k2)
; #pragma unroll
;             for (int n = 0; n < 2; ++n) { const s16x4 lo = tr16(Vl + (32 * k2 + 8 * g + q4) * RT_VS + (32 * w + 16 * n + 4 * p4) * 2), hi = tr16(Vl + (32 * k2 + 8 * g + 4 + q4) * RT_VS + (32 * w + 16 * n + 4 * p4) * 2);
;                 Bv[k2][n] = __builtin_shufflevector(lo, hi, 0, 1, 2, 3, 4, 5, 6, 7); }
; #pragma unroll
;         for (int k2 = 0; k2 < 2; ++k2)
; #pragma unroll
;             for (int m = 0; m < 4; ++m) { const bf16x8 A = *(const LAS bf16x8*)(Al + (16 * m + l15) * RT_AS + (32 * k2 + 8 * g) * 2);
; #pragma unroll
;                 for (int n = 0; n < 2; ++n) accO[m][n] = MFMA16(A, Bv[k2][n], accO[m][n]); }
.LBB0_1413:
	v_cvt_pk_bf16_f32 v102, v1, v3
	v_cvt_pk_bf16_f32 v103, v100, v101
	v_add_u32_e32 v1, v189, v186
	ds_write_b64 v215, v[102:103]
	s_waitcnt lgkmcnt(0)
	s_barrier
	v_cvt_pk_bf16_f32 v100, v84, v85
	v_cvt_pk_bf16_f32 v101, v86, v87
	v_cvt_pk_bf16_f32 v102, v88, v89
	v_cvt_pk_bf16_f32 v103, v90, v91
	v_cvt_pk_bf16_f32 v104, v92, v93
	v_cvt_pk_bf16_f32 v105, v94, v95
	v_cvt_pk_bf16_f32 v106, v96, v97
	v_cvt_pk_bf16_f32 v107, v98, v99
	ds_read_b64 v[108:109], v1
	ds_read_b64 v[110:111], v216
	ds_read_b64 v[116:117], v1 offset:4352
	ds_read_b64 v[118:119], v216 offset:4352
	ds_read_b64 v[124:125], v1 offset:8704
	ds_read_b64 v[126:127], v216 offset:8704
	ds_read_b64 v[132:133], v1 offset:13056
	ds_read_b64 v[134:135], v216 offset:13056
	s_waitcnt lgkmcnt(6)
	v_mfma_f32_16x16x32_bf16 v[112:115], v[108:111], v[100:103], 0
	v_add_u32_e32 v1, v190, v188
	s_and_b64 vcc, exec, s[38:39]
	v_mfma_f32_16x16x32_bf16 v[108:111], v[108:111], v[104:107], 0
	s_waitcnt lgkmcnt(4)
	v_mfma_f32_16x16x32_bf16 v[120:123], v[116:119], v[100:103], 0
	v_mfma_f32_16x16x32_bf16 v[116:119], v[116:119], v[104:107], 0
	s_waitcnt lgkmcnt(2)
	v_mfma_f32_16x16x32_bf16 v[128:131], v[124:127], v[100:103], 0
	v_mfma_f32_16x16x32_bf16 v[124:127], v[124:127], v[104:107], 0
	s_waitcnt lgkmcnt(0)
	v_mfma_f32_16x16x32_bf16 v[100:103], v[132:135], v[100:103], 0
	v_mfma_f32_16x16x32_bf16 v[104:107], v[132:135], v[104:107], 0
	v_cvt_pk_bf16_f32 v132, v76, v77
	v_cvt_pk_bf16_f32 v133, v78, v79
	v_cvt_pk_bf16_f32 v134, v68, v69
	v_cvt_pk_bf16_f32 v135, v70, v71
	v_cvt_pk_bf16_f32 v136, v80, v81
	v_cvt_pk_bf16_f32 v137, v82, v83
	v_cvt_pk_bf16_f32 v138, v72, v73
	v_cvt_pk_bf16_f32 v139, v74, v75
	ds_read_b64 v[140:141], v217
	ds_read_b64 v[142:143], v218
	s_waitcnt lgkmcnt(0)
	v_mfma_f32_16x16x32_bf16 v[112:115], v[140:143], v[132:135], v[112:115]
	v_mfma_f32_16x16x32_bf16 v[108:111], v[140:143], v[136:139], v[108:111]
	ds_read_b64 v[140:141], v217 offset:4352
	ds_read_b64 v[142:143], v218 offset:4352
	s_waitcnt lgkmcnt(0)
	v_mfma_f32_16x16x32_bf16 v[120:123], v[140:143], v[132:135], v[120:123]
	v_mfma_f32_16x16x32_bf16 v[116:119], v[140:143], v[136:139], v[116:119]
	ds_read_b64 v[140:141], v217 offset:8704
	ds_read_b64 v[142:143], v218 offset:8704
	s_waitcnt lgkmcnt(0)
	v_mfma_f32_16x16x32_bf16 v[128:131], v[140:143], v[132:135], v[128:131]
	v_mfma_f32_16x16x32_bf16 v[124:127], v[140:143], v[136:139], v[124:127]
	ds_read_b64 v[140:141], v217 offset:13056
	ds_read_b64 v[142:143], v218 offset:13056
	s_waitcnt lgkmcnt(0)
	v_mfma_f32_16x16x32_bf16 v[100:103], v[140:143], v[132:135], v[100:103]
	v_cvt_pk_bf16_f32 v132, v52, v53
	v_cvt_pk_bf16_f32 v133, v54, v55
	v_cvt_pk_bf16_f32 v134, v40, v41
	v_mfma_f32_16x16x32_bf16 v[104:107], v[140:143], v[136:139], v[104:107]
	v_cvt_pk_bf16_f32 v135, v42, v43
	v_cvt_pk_bf16_f32 v136, v64, v65
	v_cvt_pk_bf16_f32 v137, v66, v67
	v_cvt_pk_bf16_f32 v138, v56, v57
	v_cvt_pk_bf16_f32 v139, v58, v59
	ds_read_b64 v[140:141], v219
	ds_read_b64 v[142:143], v220
	s_waitcnt lgkmcnt(0)
	v_mfma_f32_16x16x32_bf16 v[112:115], v[140:143], v[132:135], v[112:115]
	v_mfma_f32_16x16x32_bf16 v[108:111], v[140:143], v[136:139], v[108:111]
	ds_read_b64 v[140:141], v219 offset:4352
	ds_read_b64 v[142:143], v220 offset:4352
	s_waitcnt lgkmcnt(0)
	v_mfma_f32_16x16x32_bf16 v[120:123], v[140:143], v[132:135], v[120:123]
	v_mfma_f32_16x16x32_bf16 v[116:119], v[140:143], v[136:139], v[116:119]
	ds_read_b64 v[140:141], v219 offset:8704
	ds_read_b64 v[142:143], v220 offset:8704
	s_waitcnt lgkmcnt(0)
	v_mfma_f32_16x16x32_bf16 v[128:131], v[140:143], v[132:135], v[128:131]
	v_mfma_f32_16x16x32_bf16 v[124:127], v[140:143], v[136:139], v[124:127]
	ds_read_b64 v[140:141], v219 offset:13056
	ds_read_b64 v[142:143], v220 offset:13056
	s_waitcnt lgkmcnt(0)
	v_mfma_f32_16x16x32_bf16 v[100:103], v[140:143], v[132:135], v[100:103]
	v_cvt_pk_bf16_f32 v132, v44, v45
	v_cvt_pk_bf16_f32 v133, v46, v47
	v_cvt_pk_bf16_f32 v134, v36, v37
	v_mfma_f32_16x16x32_bf16 v[104:107], v[140:143], v[136:139], v[104:107]
	v_cvt_pk_bf16_f32 v135, v38, v39
	v_cvt_pk_bf16_f32 v136, v60, v61
	v_cvt_pk_bf16_f32 v137, v62, v63
	v_cvt_pk_bf16_f32 v138, v48, v49
	v_cvt_pk_bf16_f32 v139, v50, v51
	ds_read_b64 v[140:141], v221
	ds_read_b64 v[142:143], v222
	s_waitcnt lgkmcnt(0)
	v_mfma_f32_16x16x32_bf16 v[112:115], v[140:143], v[132:135], v[112:115]
	v_mfma_f32_16x16x32_bf16 v[108:111], v[140:143], v[136:139], v[108:111]
	ds_read_b64 v[140:141], v221 offset:4352
	ds_read_b64 v[142:143], v222 offset:4352
	s_waitcnt lgkmcnt(0)
	v_mfma_f32_16x16x32_bf16 v[120:123], v[140:143], v[132:135], v[120:123]
	v_mfma_f32_16x16x32_bf16 v[116:119], v[140:143], v[136:139], v[116:119]
	ds_read_b64 v[140:141], v221 offset:8704
	ds_read_b64 v[142:143], v222 offset:8704
	s_waitcnt lgkmcnt(0)
	v_mfma_f32_16x16x32_bf16 v[144:147], v[140:143], v[132:135], v[128:131]
	v_mfma_f32_16x16x32_bf16 v[140:143], v[140:143], v[136:139], v[124:127]
	s_nop 2
	ds_read_b64 v[124:125], v221 offset:13056
	ds_read_b64 v[126:127], v222 offset:13056
	s_waitcnt lgkmcnt(0)
	v_mfma_f32_16x16x32_bf16 v[100:103], v[124:127], v[132:135], v[100:103]
	ds_read_b128 v[132:135], v224
	v_mfma_f32_16x16x32_bf16 v[104:107], v[124:127], v[136:139], v[104:107]
	ds_read_b64_tr_b16 v[126:127], v1 offset:36928
	ds_read_b64_tr_b16 v[124:125], v1 offset:34816
	ds_read_b64_tr_b16 v[128:129], v1 offset:34848
	ds_read_b64_tr_b16 v[130:131], v1 offset:36960
	v_add_u32_e32 v1, v191, v187
	s_waitcnt lgkmcnt(2)
	v_mfma_f32_16x16x32_bf16 v[136:139], v[132:135], v[124:127], v[112:115]
	s_waitcnt lgkmcnt(0)
	v_mfma_f32_16x16x32_bf16 v[132:135], v[132:135], v[128:131], v[108:111]
	s_nop 2
	ds_read_b128 v[108:111], v224 offset:2304
	s_waitcnt lgkmcnt(0)
; #define LAS __attribute__((address_space(3)))
; #define MFMA16(a, b, c) __builtin_amdgcn_mfma_f32_16x16x32_bf16((a), (b), (c), 0, 0, 0)
; __device__ __forceinline__ s16x4 tr16(const LAS unsigned char* p) { typedef short v4i16_t __attribute__((ext_vector_type(4))); return __builtin_bit_cast(s16x4, __builtin_amdgcn_ds_read_tr16_b64_v4i16((LAS v4i16_t*)p)); }
; __device__ __forceinline__ void ret_unit(const Frame& F, int layer, int uid) {
;     ...
;         bf16x8 Bv[2][2];
; #pragma unroll
;         for (int k2 = 0; k2 < 2; ++k2)
; #pragma unroll
;             for (int n = 0; n < 2; ++n) { const s16x4 lo = tr16(Vl + (32 * k2 + 8 * g + q4) * RT_VS + (32 * w + 16 * n + 4 * p4) * 2), hi = tr16(Vl + (32 * k2 + 8 * g + 4 + q4) * RT_VS + (32 * w + 16 * n + 4 * p4) * 2);
;                 Bv[k2][n] = __builtin_shufflevector(lo, hi, 0, 1, 2, 3, 4, 5, 6, 7); }
; #pragma unroll
;         for (int k2 = 0; k2 < 2; ++k2)
; #pragma unroll
;             for (int m = 0; m < 4; ++m) { const bf16x8 A = *(const LAS bf16x8*)(Al + (16 * m + l15) * RT_AS + (32 * k2 + 8 * g) * 2);
; #pragma unroll
;                 for (int n = 0; n < 2; ++n) accO[m][n] = MFMA16(A, Bv[k2][n], accO[m][n]); }
; #pragma unroll
;         for (int m = 0; m < 8; ++m)
; #pragma unroll
;             for (int k2 = 0; k2 < 2; ++k2) { const s16x4 lo = tr16(Kl + (32 * k2 + 8 * g + q4) * RT_QS + (16 * m + 4 * p4) * 2), hi = tr16(Kl + (32 * k2 + 8 * g + 4 + q4) * RT_QS + (16 * m + 4 * p4) * 2);
;                 const bf16x8 A = __builtin_shufflevector(lo, hi, 0, 1, 2, 3, 4, 5, 6, 7);
; #pragma unroll
;                 for (int n = 0; n < 2; ++n) accS[m][n] = MFMA16(A, Bv[k2][n], accS[m][n]); }
; #pragma unroll
;         for (int m = 0; m < 8; ++m)
; #pragma unroll
;             for (int n = 0; n < 2; ++n) accS[m][n] = accS[m][n] * dc;
;         if (write_out) {
	v_mfma_f32_16x16x32_bf16 v[120:123], v[108:111], v[124:127], v[120:123]
	v_mfma_f32_16x16x32_bf16 v[246:249], v[108:111], v[128:131], v[116:119]
	ds_read_b128 v[108:111], v224 offset:4608
	s_waitcnt lgkmcnt(0)
	v_mfma_f32_16x16x32_bf16 v[144:147], v[108:111], v[124:127], v[144:147]
	v_mfma_f32_16x16x32_bf16 v[140:143], v[108:111], v[128:131], v[140:143]
	ds_read_b128 v[108:111], v224 offset:6912
	ds_read_b128 v[116:119], v224 offset:64
	ds_read_b64_tr_b16 v[114:115], v223 offset:36928
	s_waitcnt lgkmcnt(2)
	v_mfma_f32_16x16x32_bf16 v[194:197], v[108:111], v[124:127], v[100:103]
	v_mfma_f32_16x16x32_bf16 v[202:205], v[108:111], v[128:131], v[104:107]
	ds_read_b64_tr_b16 v[112:113], v223 offset:34816
	ds_read_b64_tr_b16 v[108:109], v223 offset:34848
	ds_read_b64_tr_b16 v[110:111], v223 offset:36960
	s_waitcnt lgkmcnt(2)
	v_mfma_f32_16x16x32_bf16 v[100:103], v[116:119], v[112:115], v[136:139]
	s_nop 2
	ds_read_b128 v[136:139], v224 offset:4672
	s_waitcnt lgkmcnt(1)
	v_mfma_f32_16x16x32_bf16 v[104:107], v[116:119], v[108:111], v[132:135]
	s_nop 2
	ds_read_b128 v[132:135], v224 offset:2368
	s_waitcnt lgkmcnt(0)
	v_mfma_f32_16x16x32_bf16 v[116:119], v[132:135], v[112:115], v[120:123]
	v_mfma_f32_16x16x32_bf16 v[120:123], v[132:135], v[108:111], v[246:249]
	v_mfma_f32_16x16x32_bf16 v[132:135], v[136:139], v[112:115], v[144:147]
	s_nop 2
	ds_read_b128 v[144:147], v224 offset:6976
	v_mfma_f32_16x16x32_bf16 v[136:139], v[136:139], v[108:111], v[140:143]
	s_waitcnt lgkmcnt(0)
	v_mfma_f32_16x16x32_bf16 v[140:143], v[144:147], v[112:115], v[194:197]
	s_nop 2
	ds_read_b64_tr_b16 v[196:197], v1 offset:18496
	ds_read_b64_tr_b16 v[194:195], v1 offset:17408
	s_waitcnt lgkmcnt(0)
	v_mfma_f32_16x16x32_bf16 v[84:87], v[194:197], v[124:127], v[84:87]
	v_mfma_f32_16x16x32_bf16 v[92:95], v[194:197], v[128:131], v[92:95]
	ds_read_b64_tr_b16 v[196:197], v225 offset:18496
	ds_read_b64_tr_b16 v[194:195], v225 offset:17408
	v_mfma_f32_16x16x32_bf16 v[144:147], v[144:147], v[108:111], v[202:205]
	s_nop 2
	ds_read_b64_tr_b16 v[202:203], v1 offset:17440
	ds_read_b64_tr_b16 v[204:205], v1 offset:18528
	s_waitcnt lgkmcnt(2)
	v_mfma_f32_16x16x32_bf16 v[84:87], v[194:197], v[112:115], v[84:87]
	v_mfma_f32_16x16x32_bf16 v[92:95], v[194:197], v[108:111], v[92:95]
	ds_read_b64_tr_b16 v[194:195], v225 offset:17440
	ds_read_b64_tr_b16 v[196:197], v225 offset:18528
	s_waitcnt lgkmcnt(2)
	v_mfma_f32_16x16x32_bf16 v[88:91], v[202:205], v[124:127], v[88:91]
	v_mfma_f32_16x16x32_bf16 v[96:99], v[202:205], v[128:131], v[96:99]
	s_waitcnt lgkmcnt(0)
	v_mfma_f32_16x16x32_bf16 v[88:91], v[194:197], v[112:115], v[88:91]
	v_mfma_f32_16x16x32_bf16 v[96:99], v[194:197], v[108:111], v[96:99]
	ds_read_b64_tr_b16 v[194:195], v1 offset:17472
	ds_read_b64_tr_b16 v[196:197], v1 offset:18560
	s_waitcnt lgkmcnt(0)
	v_mfma_f32_16x16x32_bf16 v[76:79], v[194:197], v[124:127], v[76:79]
	v_mfma_f32_16x16x32_bf16 v[80:83], v[194:197], v[128:131], v[80:83]
	ds_read_b64_tr_b16 v[194:195], v225 offset:17472
	ds_read_b64_tr_b16 v[196:197], v225 offset:18560
	s_waitcnt lgkmcnt(0)
	v_mfma_f32_16x16x32_bf16 v[76:79], v[194:197], v[112:115], v[76:79]
	v_mfma_f32_16x16x32_bf16 v[80:83], v[194:197], v[108:111], v[80:83]
	ds_read_b64_tr_b16 v[194:195], v1 offset:17504
	ds_read_b64_tr_b16 v[196:197], v1 offset:18592
	s_waitcnt lgkmcnt(0)
	v_mfma_f32_16x16x32_bf16 v[68:71], v[194:197], v[124:127], v[68:71]
	v_mfma_f32_16x16x32_bf16 v[72:75], v[194:197], v[128:131], v[72:75]
	ds_read_b64_tr_b16 v[194:195], v225 offset:17504
	ds_read_b64_tr_b16 v[196:197], v225 offset:18592
	s_waitcnt lgkmcnt(0)
	v_mfma_f32_16x16x32_bf16 v[68:71], v[194:197], v[112:115], v[68:71]
	v_mfma_f32_16x16x32_bf16 v[72:75], v[194:197], v[108:111], v[72:75]
	ds_read_b64_tr_b16 v[194:195], v1 offset:17536
	ds_read_b64_tr_b16 v[196:197], v1 offset:18624
	s_waitcnt lgkmcnt(0)
	v_mfma_f32_16x16x32_bf16 v[52:55], v[194:197], v[124:127], v[52:55]
	v_mfma_f32_16x16x32_bf16 v[64:67], v[194:197], v[128:131], v[64:67]
	ds_read_b64_tr_b16 v[194:195], v225 offset:17536
	ds_read_b64_tr_b16 v[196:197], v225 offset:18624
	s_waitcnt lgkmcnt(0)
	v_mfma_f32_16x16x32_bf16 v[52:55], v[194:197], v[112:115], v[52:55]
	v_mfma_f32_16x16x32_bf16 v[64:67], v[194:197], v[108:111], v[64:67]
	ds_read_b64_tr_b16 v[194:195], v1 offset:17568
	ds_read_b64_tr_b16 v[196:197], v1 offset:18656
	s_waitcnt lgkmcnt(0)
	v_mfma_f32_16x16x32_bf16 v[40:43], v[194:197], v[124:127], v[40:43]
	v_mfma_f32_16x16x32_bf16 v[56:59], v[194:197], v[128:131], v[56:59]
	ds_read_b64_tr_b16 v[194:195], v225 offset:17568
	ds_read_b64_tr_b16 v[196:197], v225 offset:18656
	s_waitcnt lgkmcnt(0)
	v_mfma_f32_16x16x32_bf16 v[40:43], v[194:197], v[112:115], v[40:43]
	v_mfma_f32_16x16x32_bf16 v[56:59], v[194:197], v[108:111], v[56:59]
	ds_read_b64_tr_b16 v[194:195], v1 offset:17600
	ds_read_b64_tr_b16 v[196:197], v1 offset:18688
	s_waitcnt lgkmcnt(0)
	v_mfma_f32_16x16x32_bf16 v[44:47], v[194:197], v[124:127], v[44:47]
	v_mfma_f32_16x16x32_bf16 v[60:63], v[194:197], v[128:131], v[60:63]
	ds_read_b64_tr_b16 v[194:195], v225 offset:17600
	ds_read_b64_tr_b16 v[196:197], v225 offset:18688
	s_waitcnt lgkmcnt(0)
	v_mfma_f32_16x16x32_bf16 v[44:47], v[194:197], v[112:115], v[44:47]
	v_mfma_f32_16x16x32_bf16 v[60:63], v[194:197], v[108:111], v[60:63]
	ds_read_b64_tr_b16 v[194:195], v1 offset:17632
	ds_read_b64_tr_b16 v[196:197], v1 offset:18720
	s_waitcnt lgkmcnt(0)
	v_mfma_f32_16x16x32_bf16 v[36:39], v[194:197], v[124:127], v[36:39]
	ds_read_b64_tr_b16 v[124:125], v225 offset:17632
	ds_read_b64_tr_b16 v[126:127], v225 offset:18720
	v_mfma_f32_16x16x32_bf16 v[48:51], v[194:197], v[128:131], v[48:51]
	s_waitcnt lgkmcnt(0)
	v_mfma_f32_16x16x32_bf16 v[36:39], v[124:127], v[112:115], v[36:39]
	v_mfma_f32_16x16x32_bf16 v[48:51], v[124:127], v[108:111], v[48:51]
	s_cbranch_vccnz .LBB0_1380
; #define GAS __attribute__((address_space(1)))
; #define LAS __attribute__((address_space(3)))
; __device__ __forceinline__ void ret_unit(const Frame& F, int layer, int uid) {
;     ...
;             __syncthreads();
;             LAS float* oL = (LAS float*)F.lds;
; #pragma unroll
;             for (int m = 0; m < 4; ++m)
; #pragma unroll
;                 for (int n = 0; n < 2; ++n)
; #pragma unroll
;                     for (int r = 0; r < 4; ++r) oL[(16 * m + 4 * g + r) * 256 + 32 * w + 16 * n + l15] = accO[m][n][r];
;             __syncthreads();
;             const f32x4 gn = *(const GAS f32x4*)(in_ptr(IN_RETG) + ((size_t)layer * HRET + h) * DVR + lane * 4);
; #pragma unroll
;             for (int hb2 = 0; hb2 < 2; ++hb2) {
;             f32x4 x[4]; v2u gr[4]; float s1[4], s2[4];
; #pragma unroll
;             for (int tt = 0; tt < 4; ++tt) { const int t = w * 8 + hb2 * 4 + tt; x[tt] = *(const LAS f32x4*)(oL + t * 256 + lane * 4); gr[tt] = grp[hb2][tt];
;                 s1[tt] = (x[tt][0] + x[tt][1]) + (x[tt][2] + x[tt][3]); }
; #pragma unroll
;             for (int o = 1; o < 64; o <<= 1)
; #pragma unroll
;                 for (int tt = 0; tt < 4; ++tt) s1[tt] += __shfl_xor(s1[tt], o);
; #pragma unroll
;             for (int tt = 0; tt < 4; ++tt) { x[tt] = x[tt] - s1[tt] * (1.f / 256.f); s2[tt] = (x[tt][0] * x[tt][0] + x[tt][1] * x[tt][1]) + (x[tt][2] * x[tt][2] + x[tt][3] * x[tt][3]); }
	v_add_u32_e32 v1, 0x400, v226
	s_barrier
	ds_write2_b32 v1, v101, v105 offset1:16
	v_add_u32_e32 v1, 0x800, v226
	ds_write2_b32 v1, v102, v106 offset1:16
	v_add_u32_e32 v1, 0xc00, v226
	ds_write2_b32 v226, v100, v104 offset1:16
	ds_write2_b32 v1, v103, v107 offset1:16
	ds_write2_b32 v227, v116, v120 offset1:16
	v_add_u32_e32 v1, 0x4400, v226
	ds_write2_b32 v1, v117, v121 offset1:16
	v_add_u32_e32 v1, 0x4800, v226
	ds_write2_b32 v1, v118, v122 offset1:16
	v_add_u32_e32 v1, 0x4c00, v226
	ds_write2_b32 v1, v119, v123 offset1:16
	ds_write2_b32 v228, v132, v136 offset1:16
	v_add_u32_e32 v1, 0x8400, v226
	ds_write2_b32 v1, v133, v137 offset1:16
	v_add_u32_e32 v1, 0x8800, v226
	ds_write2_b32 v1, v134, v138 offset1:16
	v_add_u32_e32 v1, 0x8c00, v226
	ds_write2_b32 v1, v135, v139 offset1:16
	ds_write2_b32 v229, v140, v144 offset1:16
	v_add_u32_e32 v1, 0xc400, v226
	ds_write2_b32 v1, v141, v145 offset1:16
	v_add_u32_e32 v1, 0xc800, v226
	ds_write2_b32 v1, v142, v146 offset1:16
	v_add_u32_e32 v1, 0xcc00, v226
	s_mov_b64 s[38:39], s[0:1]
	ds_write2_b32 v1, v143, v147 offset1:16
	s_waitcnt lgkmcnt(0)
	s_barrier
	s_load_dwordx2 s[38:39], s[38:39], 0x40
	v_and_b32_e32 v1, 64, v239
	v_add_u32_e32 v124, 64, v1
	s_waitcnt lgkmcnt(0)
	s_add_u32 s38, s38, s68
	s_addc_u32 s39, s39, s69
	v_lshl_add_u64 v[100:101], v[166:167], 2, s[38:39]
	v_readlane_b32 s38, v253, 33
	global_load_dwordx4 v[100:103], v[100:101], off
	s_cmp_ge_u32 s70, s67
	v_add_u32_e32 v1, s38, v192
	ds_read_b128 v[116:119], v1
	v_readlane_b32 s38, v253, 45
	s_waitcnt lgkmcnt(0)
	v_mov_b32_e32 v104, v117
	v_add_u32_e32 v1, s38, v192
	ds_read_b128 v[112:115], v1
	v_readlane_b32 s38, v253, 47
	v_mov_b32_e32 v105, v118
	v_mov_b32_e32 v106, v116
	v_add_u32_e32 v1, s38, v192
	ds_read_b128 v[108:111], v1
	v_mov_b32_e32 v107, v119
	v_pk_add_f32 v[104:105], v[104:105], v[106:107]
	s_waitcnt lgkmcnt(1)
	v_mov_b32_e32 v106, v112
	v_add_f32_e32 v3, v104, v105
	v_mov_b32_e32 v104, v113
	v_mov_b32_e32 v105, v114
	v_mov_b32_e32 v107, v115
	v_pk_add_f32 v[104:105], v[104:105], v[106:107]
	s_waitcnt lgkmcnt(0)
	v_mov_b32_e32 v106, v108
	v_add_f32_e32 v125, v104, v105
	v_mov_b32_e32 v104, v109
	v_mov_b32_e32 v105, v110
	v_mov_b32_e32 v107, v111
	v_readlane_b32 s38, v253, 48
	v_pk_add_f32 v[104:105], v[104:105], v[106:107]
	s_nop 0
	v_add_u32_e32 v1, s38, v192
	v_add_f32_e32 v126, v104, v105
	ds_read_b128 v[104:107], v1
	v_xor_b32_e32 v1, 1, v239
	v_cmp_lt_i32_e32 vcc, v1, v124
	s_waitcnt lgkmcnt(0)
	v_mov_b32_e32 v120, v105
	v_mov_b32_e32 v121, v106
	v_mov_b32_e32 v122, v104
	v_mov_b32_e32 v123, v107
	v_cndmask_b32_e32 v1, v239, v1, vcc
	v_pk_add_f32 v[120:121], v[120:121], v[122:123]
	v_lshlrev_b32_e32 v1, 2, v1
	v_add_f32_e32 v120, v120, v121
	ds_bpermute_b32 v194, v1, v3
	ds_bpermute_b32 v195, v1, v125
	ds_bpermute_b32 v196, v1, v126
	ds_bpermute_b32 v197, v1, v120
	s_waitcnt lgkmcnt(3)
	v_add_f32_e32 v121, v3, v194
	s_waitcnt lgkmcnt(2)
	v_add_f32_e32 v122, v125, v195
	s_waitcnt lgkmcnt(1)
	v_add_f32_e32 v123, v126, v196
	s_waitcnt lgkmcnt(0)
	v_add_f32_e32 v120, v120, v197
	v_xor_b32_e32 v3, 2, v239
	v_cmp_lt_i32_e32 vcc, v3, v124
	s_nop 1
	v_cndmask_b32_e32 v3, v239, v3, vcc
	v_lshlrev_b32_e32 v3, 2, v3
	ds_bpermute_b32 v194, v3, v121
	ds_bpermute_b32 v195, v3, v122
	ds_bpermute_b32 v196, v3, v123
	ds_bpermute_b32 v197, v3, v120
	s_waitcnt lgkmcnt(3)
	v_add_f32_e32 v121, v121, v194
	s_waitcnt lgkmcnt(2)
	v_add_f32_e32 v122, v122, v195
	s_waitcnt lgkmcnt(1)
	v_add_f32_e32 v123, v123, v196
	s_waitcnt lgkmcnt(0)
	v_add_f32_e32 v125, v120, v197
	v_xor_b32_e32 v120, 4, v239
	v_cmp_lt_i32_e32 vcc, v120, v124
	s_nop 1
	v_cndmask_b32_e32 v120, v239, v120, vcc
	v_lshlrev_b32_e32 v120, 2, v120
	ds_bpermute_b32 v194, v120, v121
	ds_bpermute_b32 v195, v120, v122
	ds_bpermute_b32 v196, v120, v123
	ds_bpermute_b32 v197, v120, v125
	s_waitcnt lgkmcnt(3)
	v_add_f32_e32 v126, v121, v194
	s_waitcnt lgkmcnt(2)
	v_add_f32_e32 v122, v122, v195
	s_waitcnt lgkmcnt(1)
	v_add_f32_e32 v123, v123, v196
	s_waitcnt lgkmcnt(0)
	v_add_f32_e32 v125, v125, v197
	v_xor_b32_e32 v121, 8, v239
	v_cmp_lt_i32_e32 vcc, v121, v124
	s_nop 1
	v_cndmask_b32_e32 v121, v239, v121, vcc
	v_lshlrev_b32_e32 v121, 2, v121
	ds_bpermute_b32 v194, v121, v126
	ds_bpermute_b32 v195, v121, v122
	ds_bpermute_b32 v196, v121, v123
	ds_bpermute_b32 v197, v121, v125
	s_waitcnt lgkmcnt(3)
	v_add_f32_e32 v126, v126, v194
	s_waitcnt lgkmcnt(2)
	v_add_f32_e32 v127, v122, v195
	s_waitcnt lgkmcnt(1)
	v_add_f32_e32 v123, v123, v196
	s_waitcnt lgkmcnt(0)
	v_add_f32_e32 v125, v125, v197
	v_xor_b32_e32 v122, 16, v239
	v_cmp_lt_i32_e32 vcc, v122, v124
	s_nop 1
	v_cndmask_b32_e32 v122, v239, v122, vcc
	v_lshlrev_b32_e32 v122, 2, v122
	ds_bpermute_b32 v194, v122, v126
	ds_bpermute_b32 v195, v122, v127
	ds_bpermute_b32 v196, v122, v123
	ds_bpermute_b32 v197, v122, v125
	s_waitcnt lgkmcnt(3)
	v_add_f32_e32 v126, v126, v194
	s_waitcnt lgkmcnt(2)
	v_add_f32_e32 v127, v127, v195
	s_waitcnt lgkmcnt(1)
	v_add_f32_e32 v128, v123, v196
	s_waitcnt lgkmcnt(0)
	v_add_f32_e32 v125, v125, v197
	v_xor_b32_e32 v123, 32, v239
	v_cmp_lt_i32_e32 vcc, v123, v124
	s_nop 1
	v_cndmask_b32_e32 v123, v239, v123, vcc
	v_lshlrev_b32_e32 v123, 2, v123
	ds_bpermute_b32 v124, v123, v126
	s_waitcnt lgkmcnt(0)
	v_add_f32_e32 v124, v126, v124
	ds_bpermute_b32 v126, v123, v127
	v_fmamk_f32 v119, v124, 0xbb800000, v119
	v_fmamk_f32 v117, v124, 0xbb800000, v117
	v_fmamk_f32 v118, v124, 0xbb800000, v118
	v_fmac_f32_e32 v116, 0xbb800000, v124
	s_waitcnt lgkmcnt(0)
	v_add_f32_e32 v126, v127, v126
	ds_bpermute_b32 v127, v123, v128
	v_mul_f32_e32 v124, v117, v117
	v_fmac_f32_e32 v124, v116, v116
	v_fmamk_f32 v115, v126, 0xbb800000, v115
	v_fmamk_f32 v113, v126, 0xbb800000, v113
	s_waitcnt lgkmcnt(0)
; #define GAS __attribute__((address_space(1)))
; __device__ __forceinline__ unsigned pk2(float lo, float hi) { return f2bf(lo) | (f2bf(hi) << 16); }
; #define WSB(F, off) ((bf16*)(wsq((F).ws) + (off)))
; __device__ __forceinline__ void ret_unit(const Frame& F, int layer, int uid) {
;     ...
;             for (int tt = 0; tt < 4; ++tt) { x[tt] = x[tt] - s1[tt] * (1.f / 256.f); s2[tt] = (x[tt][0] * x[tt][0] + x[tt][1] * x[tt][1]) + (x[tt][2] * x[tt][2] + x[tt][3] * x[tt][3]); }
; #pragma unroll
;             for (int o = 1; o < 64; o <<= 1)
; #pragma unroll
;                 for (int tt = 0; tt < 4; ++tt) s2[tt] += __shfl_xor(s2[tt], o);
; #pragma unroll
;             for (int tt = 0; tt < 4; ++tt) { const int t = w * 8 + hb2 * 4 + tt; const float rstd = 1.f / sqrtf(s2[tt] * (1.f / 256.f) + LN_EPS);
;                 const f32x4 y = x[tt] * rstd * gn * (f32x4){bflo(gr[tt].x), bfhi(gr[tt].x), bflo(gr[tt].y), bfhi(gr[tt].y)};
;                 if (t < valid) *(GAS v2u*)(WSB(F, WS_BR) + (size_t)(rowbase + t) * D + h * 256 + lane * 4) = (v2u){pk2(y[0], y[1]), pk2(y[2], y[3])}; }
	v_add_f32_e32 v127, v128, v127
	ds_bpermute_b32 v128, v123, v125
	v_fmamk_f32 v114, v126, 0xbb800000, v114
	v_fmac_f32_e32 v112, 0xbb800000, v126
	v_mul_f32_e32 v126, v113, v113
	v_fmac_f32_e32 v126, v112, v112
	s_waitcnt lgkmcnt(0)
	v_add_f32_e32 v125, v125, v128
	v_mul_f32_e32 v128, v119, v119
	v_fmac_f32_e32 v128, v118, v118
	v_add_f32_e32 v124, v124, v128
	v_mul_f32_e32 v128, v115, v115
	v_fmac_f32_e32 v128, v114, v114
	v_fmamk_f32 v111, v127, 0xbb800000, v111
	v_fmamk_f32 v109, v127, 0xbb800000, v109
	v_add_f32_e32 v126, v126, v128
	v_fmamk_f32 v110, v127, 0xbb800000, v110
	v_fmac_f32_e32 v108, 0xbb800000, v127
	v_mul_f32_e32 v127, v109, v109
	v_mul_f32_e32 v128, v111, v111
	v_fmac_f32_e32 v127, v108, v108
	v_fmac_f32_e32 v128, v110, v110
	v_fmamk_f32 v107, v125, 0xbb800000, v107
	v_fmamk_f32 v105, v125, 0xbb800000, v105
	v_add_f32_e32 v127, v127, v128
	v_fmamk_f32 v106, v125, 0xbb800000, v106
	v_fmac_f32_e32 v104, 0xbb800000, v125
	v_mul_f32_e32 v125, v105, v105
	v_mul_f32_e32 v128, v107, v107
	v_fmac_f32_e32 v125, v104, v104
	v_fmac_f32_e32 v128, v106, v106
	v_add_f32_e32 v125, v125, v128
	ds_bpermute_b32 v194, v1, v124
	ds_bpermute_b32 v195, v1, v126
	ds_bpermute_b32 v196, v1, v127
	ds_bpermute_b32 v197, v1, v125
	s_waitcnt lgkmcnt(3)
	v_add_f32_e32 v124, v124, v194
	s_waitcnt lgkmcnt(2)
	v_add_f32_e32 v126, v126, v195
	s_waitcnt lgkmcnt(1)
	v_add_f32_e32 v127, v127, v196
	s_waitcnt lgkmcnt(0)
	v_add_f32_e32 v125, v125, v197
	ds_bpermute_b32 v194, v3, v124
	ds_bpermute_b32 v195, v3, v126
	ds_bpermute_b32 v196, v3, v127
	ds_bpermute_b32 v197, v3, v125
	s_waitcnt lgkmcnt(3)
	v_add_f32_e32 v124, v124, v194
	s_waitcnt lgkmcnt(2)
	v_add_f32_e32 v126, v126, v195
	s_waitcnt lgkmcnt(1)
	v_add_f32_e32 v127, v127, v196
	s_waitcnt lgkmcnt(0)
	v_add_f32_e32 v125, v125, v197
	ds_bpermute_b32 v194, v120, v124
	ds_bpermute_b32 v195, v120, v126
	ds_bpermute_b32 v196, v120, v127
	ds_bpermute_b32 v197, v120, v125
	s_waitcnt lgkmcnt(3)
	v_add_f32_e32 v124, v124, v194
	s_waitcnt lgkmcnt(2)
	v_add_f32_e32 v126, v126, v195
	s_waitcnt lgkmcnt(1)
	v_add_f32_e32 v127, v127, v196
	s_waitcnt lgkmcnt(0)
	v_add_f32_e32 v125, v125, v197
	ds_bpermute_b32 v194, v121, v124
	ds_bpermute_b32 v195, v121, v126
	ds_bpermute_b32 v196, v121, v127
	ds_bpermute_b32 v197, v121, v125
	s_waitcnt lgkmcnt(3)
	v_add_f32_e32 v124, v124, v194
	s_waitcnt lgkmcnt(2)
	v_add_f32_e32 v126, v126, v195
	s_waitcnt lgkmcnt(1)
	v_add_f32_e32 v127, v127, v196
	s_waitcnt lgkmcnt(0)
	v_add_f32_e32 v125, v125, v197
	ds_bpermute_b32 v128, v122, v124
	s_waitcnt lgkmcnt(0)
	v_add_f32_e32 v130, v124, v128
	ds_bpermute_b32 v124, v122, v126
	ds_bpermute_b32 v131, v123, v130
	s_waitcnt lgkmcnt(1)
	v_add_f32_e32 v128, v126, v124
	ds_bpermute_b32 v124, v122, v127
	ds_bpermute_b32 v129, v123, v128
	s_waitcnt lgkmcnt(1)
	v_add_f32_e32 v126, v127, v124
	ds_bpermute_b32 v124, v122, v125
	ds_bpermute_b32 v127, v123, v126
	s_waitcnt lgkmcnt(1)
	v_add_f32_e32 v124, v125, v124
	ds_bpermute_b32 v125, v123, v124
	s_waitcnt vmcnt(0)
	s_cbranch_scc1 .LBB0_1416
	v_add_f32_e32 v130, v130, v131
	v_fmamk_f32 v130, v130, 0x3b800000, v235
	v_mul_f32_e32 v131, 0x4f800000, v130
	v_cmp_gt_f32_e32 vcc, s89, v130
	s_ashr_i32 s43, s42, 31
	s_lshl_b64 s[42:43], s[42:43], 11
	v_cndmask_b32_e32 v130, v130, v131, vcc
	v_sqrt_f32_e32 v132, v130
	s_nop 0
	v_and_b32_e32 v131, 0xffff0000, v185
	v_add_u32_e32 v133, -1, v132
	v_fma_f32 v134, -v133, v132, v130
	v_cmp_ge_f32_e64 s[38:39], 0, v134
	v_add_u32_e32 v134, 1, v132
	s_nop 0
	v_cndmask_b32_e64 v133, v132, v133, s[38:39]
	v_fma_f32 v132, -v134, v132, v130
	v_cmp_lt_f32_e64 s[38:39], 0, v132
	s_nop 1
	v_cndmask_b32_e64 v132, v133, v134, s[38:39]
	v_mul_f32_e32 v133, 0x37800000, v132
	v_cndmask_b32_e32 v132, v132, v133, vcc
	v_cmp_class_f32_e32 vcc, v130, v236
	v_and_b32_e32 v133, 0xffff0000, v184
	s_nop 0
	v_cndmask_b32_e32 v134, v132, v130, vcc
	v_div_scale_f32 v135, s[38:39], v134, v134, 1.0
	v_rcp_f32_e32 v136, v135
	v_lshlrev_b32_e32 v132, 16, v184
	v_lshlrev_b32_e32 v130, 16, v185
	s_mov_b64 s[38:39], s[46:47]
	v_fma_f32 v137, -v135, v136, 1.0
	v_fmac_f32_e32 v136, v137, v136
	v_div_scale_f32 v137, vcc, 1.0, v134, 1.0
	v_mul_f32_e32 v138, v137, v136
	v_fma_f32 v139, -v135, v138, v137
	v_fmac_f32_e32 v138, v139, v136
	v_fma_f32 v135, -v135, v138, v137
	v_div_fmas_f32 v135, v135, v136, v138
	v_div_fixup_f32 v134, v135, v134, 1.0
	v_pk_mul_f32 v[116:117], v[116:117], v[134:135] op_sel_hi:[1,0]
	v_pk_mul_f32 v[118:119], v[118:119], v[134:135] op_sel_hi:[1,0]
	s_nop 0
	v_pk_mul_f32 v[116:117], v[100:101], v[116:117]
	v_pk_mul_f32 v[118:119], v[102:103], v[118:119]
	v_pk_mul_f32 v[116:117], v[116:117], v[132:133]
	v_pk_mul_f32 v[118:119], v[118:119], v[130:131]
	v_bfe_u32 v130, v116, 16, 1
	v_add3_u32 v116, v116, v130, s72
	v_bfe_u32 v130, v117, 16, 1
	v_lshrrev_b32_e32 v116, 16, v116
	v_add3_u32 v117, v117, v130, s72
	s_add_u32 s38, s38, s42
	v_and_or_b32 v116, v117, s88, v116
	v_bfe_u32 v117, v118, 16, 1
	s_addc_u32 s39, s39, s43
	s_lshl_b32 s42, s52, 1
	v_add3_u32 v117, v118, v117, s72
	v_bfe_u32 v118, v119, 16, 1
	s_add_u32 s38, s38, s42
	v_lshrrev_b32_e32 v117, 16, v117
	v_add3_u32 v118, v119, v118, s72
	s_addc_u32 s39, s39, 0
	v_and_or_b32 v117, v118, s88, v117
	v_lshl_add_u64 v[118:119], v[166:167], 1, s[38:39]
	v_add_co_u32_e32 v118, vcc, 0x76fc0000, v118
	s_nop 1
	v_addc_co_u32_e32 v119, vcc, 0, v119, vcc
	global_store_dwordx2 v[118:119], v[116:117], off
; #define GAS __attribute__((address_space(1)))
; __device__ __forceinline__ unsigned pk2(float lo, float hi) { return f2bf(lo) | (f2bf(hi) << 16); }
; #define WSB(F, off) ((bf16*)(wsq((F).ws) + (off)))
; __device__ __forceinline__ void ret_unit(const Frame& F, int layer, int uid) {
;     ...
;             for (int tt = 0; tt < 4; ++tt) { const int t = w * 8 + hb2 * 4 + tt; const float rstd = 1.f / sqrtf(s2[tt] * (1.f / 256.f) + LN_EPS);
;                 const f32x4 y = x[tt] * rstd * gn * (f32x4){bflo(gr[tt].x), bfhi(gr[tt].x), bflo(gr[tt].y), bfhi(gr[tt].y)};
;                 if (t < valid) *(GAS v2u*)(WSB(F, WS_BR) + (size_t)(rowbase + t) * D + h * 256 + lane * 4) = (v2u){pk2(y[0], y[1]), pk2(y[2], y[3])}; }
.LBB0_1416:
	v_readlane_b32 s38, v253, 44
	s_cmp_ge_u32 s38, s67
	s_cbranch_scc1 .LBB0_1418
	v_add_f32_e32 v116, v128, v129
	v_fmamk_f32 v116, v116, 0x3b800000, v235
	v_mul_f32_e32 v117, 0x4f800000, v116
	v_cmp_gt_f32_e32 vcc, s89, v116
	v_readlane_b32 s42, v253, 44
	s_add_i32 s42, s78, s42
	v_cndmask_b32_e32 v116, v116, v117, vcc
	v_sqrt_f32_e32 v118, v116
	s_nop 0
	v_and_b32_e32 v117, 0xffff0000, v181
	s_ashr_i32 s43, s42, 31
	s_lshl_b64 s[42:43], s[42:43], 11
	v_add_u32_e32 v119, -1, v118
	v_fma_f32 v128, -v119, v118, v116
	v_cmp_ge_f32_e64 s[38:39], 0, v128
	v_add_u32_e32 v128, 1, v118
	s_nop 0
	v_cndmask_b32_e64 v119, v118, v119, s[38:39]
	v_fma_f32 v118, -v128, v118, v116
	v_cmp_lt_f32_e64 s[38:39], 0, v118
	s_nop 1
	v_cndmask_b32_e64 v118, v119, v128, s[38:39]
	v_mul_f32_e32 v119, 0x37800000, v118
	v_cndmask_b32_e32 v118, v118, v119, vcc
	v_cmp_class_f32_e32 vcc, v116, v236
	v_and_b32_e32 v119, 0xffff0000, v180
	s_nop 0
	v_cndmask_b32_e32 v128, v118, v116, vcc
	v_div_scale_f32 v129, s[38:39], v128, v128, 1.0
	v_rcp_f32_e32 v130, v129
	v_lshlrev_b32_e32 v118, 16, v180
	v_lshlrev_b32_e32 v116, 16, v181
	s_mov_b64 s[38:39], s[46:47]
	v_fma_f32 v131, -v129, v130, 1.0
	v_fmac_f32_e32 v130, v131, v130
	v_div_scale_f32 v131, vcc, 1.0, v128, 1.0
	v_mul_f32_e32 v132, v131, v130
	v_fma_f32 v133, -v129, v132, v131
	v_fmac_f32_e32 v132, v133, v130
	v_fma_f32 v129, -v129, v132, v131
	v_div_fmas_f32 v129, v129, v130, v132
	v_div_fixup_f32 v128, v129, v128, 1.0
	v_pk_mul_f32 v[112:113], v[112:113], v[128:129] op_sel_hi:[1,0]
	v_pk_mul_f32 v[114:115], v[114:115], v[128:129] op_sel_hi:[1,0]
	s_nop 0
	v_pk_mul_f32 v[112:113], v[100:101], v[112:113]
	v_pk_mul_f32 v[114:115], v[102:103], v[114:115]
	v_pk_mul_f32 v[112:113], v[112:113], v[118:119]
	v_pk_mul_f32 v[114:115], v[114:115], v[116:117]
	v_bfe_u32 v116, v112, 16, 1
	v_add3_u32 v112, v112, v116, s72
	v_bfe_u32 v116, v113, 16, 1
	v_lshrrev_b32_e32 v112, 16, v112
	v_add3_u32 v113, v113, v116, s72
	s_add_u32 s38, s38, s42
	v_and_or_b32 v112, v113, s88, v112
	v_bfe_u32 v113, v114, 16, 1
	s_addc_u32 s39, s39, s43
	s_lshl_b32 s42, s52, 1
	v_add3_u32 v113, v114, v113, s72
	v_bfe_u32 v114, v115, 16, 1
	s_add_u32 s38, s38, s42
	v_lshrrev_b32_e32 v113, 16, v113
	v_add3_u32 v114, v115, v114, s72
	s_addc_u32 s39, s39, 0
	v_and_or_b32 v113, v114, s88, v113
	v_lshl_add_u64 v[114:115], v[166:167], 1, s[38:39]
	v_add_co_u32_e32 v114, vcc, 0x76fc0000, v114
	s_nop 1
	v_addc_co_u32_e32 v115, vcc, 0, v115, vcc
	global_store_dwordx2 v[114:115], v[112:113], off
.LBB0_1418:
	v_readlane_b32 s38, v253, 46
	s_cmp_ge_u32 s38, s67
	s_cbranch_scc1 .LBB0_1420
	s_waitcnt lgkmcnt(1)
	v_add_f32_e32 v112, v126, v127
	v_fmamk_f32 v112, v112, 0x3b800000, v235
	v_mul_f32_e32 v113, 0x4f800000, v112
	v_cmp_gt_f32_e32 vcc, s89, v112
	v_readlane_b32 s42, v253, 46
	s_add_i32 s42, s78, s42
	v_cndmask_b32_e32 v112, v112, v113, vcc
	v_sqrt_f32_e32 v114, v112
	s_nop 0
	v_and_b32_e32 v113, 0xffff0000, v177
	s_ashr_i32 s43, s42, 31
	s_lshl_b64 s[42:43], s[42:43], 11
	v_add_u32_e32 v115, -1, v114
	v_fma_f32 v116, -v115, v114, v112
	v_cmp_ge_f32_e64 s[38:39], 0, v116
	v_add_u32_e32 v116, 1, v114
	s_nop 0
	v_cndmask_b32_e64 v115, v114, v115, s[38:39]
	v_fma_f32 v114, -v116, v114, v112
	v_cmp_lt_f32_e64 s[38:39], 0, v114
	s_nop 1
	v_cndmask_b32_e64 v114, v115, v116, s[38:39]
	v_mul_f32_e32 v115, 0x37800000, v114
	v_cndmask_b32_e32 v114, v114, v115, vcc
	v_cmp_class_f32_e32 vcc, v112, v236
	v_and_b32_e32 v115, 0xffff0000, v176
	s_nop 0
	v_cndmask_b32_e32 v116, v114, v112, vcc
	v_div_scale_f32 v117, s[38:39], v116, v116, 1.0
	v_rcp_f32_e32 v118, v117
	v_lshlrev_b32_e32 v114, 16, v176
	v_lshlrev_b32_e32 v112, 16, v177
	s_mov_b64 s[38:39], s[46:47]
	v_fma_f32 v119, -v117, v118, 1.0
	v_fmac_f32_e32 v118, v119, v118
	v_div_scale_f32 v119, vcc, 1.0, v116, 1.0
	v_mul_f32_e32 v126, v119, v118
	v_fma_f32 v127, -v117, v126, v119
	v_fmac_f32_e32 v126, v127, v118
	v_fma_f32 v117, -v117, v126, v119
	v_div_fmas_f32 v117, v117, v118, v126
	v_div_fixup_f32 v116, v117, v116, 1.0
	v_pk_mul_f32 v[108:109], v[108:109], v[116:117] op_sel_hi:[1,0]
	v_pk_mul_f32 v[110:111], v[110:111], v[116:117] op_sel_hi:[1,0]
	s_nop 0
	v_pk_mul_f32 v[108:109], v[100:101], v[108:109]
	v_pk_mul_f32 v[110:111], v[102:103], v[110:111]
	v_pk_mul_f32 v[108:109], v[108:109], v[114:115]
	v_pk_mul_f32 v[110:111], v[110:111], v[112:113]
	v_bfe_u32 v112, v108, 16, 1
	v_add3_u32 v108, v108, v112, s72
	v_bfe_u32 v112, v109, 16, 1
	v_lshrrev_b32_e32 v108, 16, v108
	v_add3_u32 v109, v109, v112, s72
	s_add_u32 s38, s38, s42
	v_and_or_b32 v108, v109, s88, v108
	v_bfe_u32 v109, v110, 16, 1
	s_addc_u32 s39, s39, s43
	s_lshl_b32 s42, s52, 1
	v_add3_u32 v109, v110, v109, s72
	v_bfe_u32 v110, v111, 16, 1
	s_add_u32 s38, s38, s42
	v_lshrrev_b32_e32 v109, 16, v109
	v_add3_u32 v110, v111, v110, s72
	s_addc_u32 s39, s39, 0
	v_and_or_b32 v109, v110, s88, v109
	v_lshl_add_u64 v[110:111], v[166:167], 1, s[38:39]
	v_add_co_u32_e32 v110, vcc, 0x76fc0000, v110
	s_nop 1
	v_addc_co_u32_e32 v111, vcc, 0, v111, vcc
	global_store_dwordx2 v[110:111], v[108:109], off
; #define GAS __attribute__((address_space(1)))
; #define LAS __attribute__((address_space(3)))
; __device__ __forceinline__ unsigned pk2(float lo, float hi) { return f2bf(lo) | (f2bf(hi) << 16); }
; #define WSB(F, off) ((bf16*)(wsq((F).ws) + (off)))
; __device__ __forceinline__ void ret_unit(const Frame& F, int layer, int uid) {
;     ...
;             for (int hb2 = 0; hb2 < 2; ++hb2) {
;             f32x4 x[4]; v2u gr[4]; float s1[4], s2[4];
; #pragma unroll
;             for (int tt = 0; tt < 4; ++tt) { const int t = w * 8 + hb2 * 4 + tt; x[tt] = *(const LAS f32x4*)(oL + t * 256 + lane * 4); gr[tt] = grp[hb2][tt];
;                 s1[tt] = (x[tt][0] + x[tt][1]) + (x[tt][2] + x[tt][3]); }
; #pragma unroll
;             for (int o = 1; o < 64; o <<= 1)
; #pragma unroll
;                 for (int tt = 0; tt < 4; ++tt) s1[tt] += __shfl_xor(s1[tt], o);
; #pragma unroll
;             for (int tt = 0; tt < 4; ++tt) { x[tt] = x[tt] - s1[tt] * (1.f / 256.f); s2[tt] = (x[tt][0] * x[tt][0] + x[tt][1] * x[tt][1]) + (x[tt][2] * x[tt][2] + x[tt][3] * x[tt][3]); }
; #pragma unroll
;             for (int o = 1; o < 64; o <<= 1)
; #pragma unroll
;                 for (int tt = 0; tt < 4; ++tt) s2[tt] += __shfl_xor(s2[tt], o);
; #pragma unroll
;             for (int tt = 0; tt < 4; ++tt) { const int t = w * 8 + hb2 * 4 + tt; const float rstd = 1.f / sqrtf(s2[tt] * (1.f / 256.f) + LN_EPS);
;                 const f32x4 y = x[tt] * rstd * gn * (f32x4){bflo(gr[tt].x), bfhi(gr[tt].x), bflo(gr[tt].y), bfhi(gr[tt].y)};
;                 if (t < valid) *(GAS v2u*)(WSB(F, WS_BR) + (size_t)(rowbase + t) * D + h * 256 + lane * 4) = (v2u){pk2(y[0], y[1]), pk2(y[2], y[3])}; }
.LBB0_1420:
	s_cmp_ge_u32 s66, s67
	s_cbranch_scc1 .LBB0_1422
	s_waitcnt lgkmcnt(0)
	v_add_f32_e32 v108, v124, v125
	v_fmamk_f32 v108, v108, 0x3b800000, v235
	v_mul_f32_e32 v109, 0x4f800000, v108
	v_cmp_gt_f32_e32 vcc, s89, v108
	s_add_i32 s42, s78, s66
	s_ashr_i32 s43, s42, 31
	v_cndmask_b32_e32 v108, v108, v109, vcc
	v_sqrt_f32_e32 v110, v108
	s_nop 0
	v_and_b32_e32 v109, 0xffff0000, v179
	s_lshl_b64 s[42:43], s[42:43], 11
	v_add_u32_e32 v111, -1, v110
	v_fma_f32 v112, -v111, v110, v108
	v_cmp_ge_f32_e64 s[38:39], 0, v112
	v_add_u32_e32 v112, 1, v110
	s_nop 0
	v_cndmask_b32_e64 v111, v110, v111, s[38:39]
	v_fma_f32 v110, -v112, v110, v108
	v_cmp_lt_f32_e64 s[38:39], 0, v110
	s_nop 1
	v_cndmask_b32_e64 v110, v111, v112, s[38:39]
	v_mul_f32_e32 v111, 0x37800000, v110
	v_cndmask_b32_e32 v110, v110, v111, vcc
	v_cmp_class_f32_e32 vcc, v108, v236
	v_and_b32_e32 v111, 0xffff0000, v178
	s_nop 0
	v_cndmask_b32_e32 v112, v110, v108, vcc
	v_div_scale_f32 v113, s[38:39], v112, v112, 1.0
	v_rcp_f32_e32 v114, v113
	v_lshlrev_b32_e32 v110, 16, v178
	v_lshlrev_b32_e32 v108, 16, v179
	s_mov_b64 s[38:39], s[46:47]
	v_fma_f32 v115, -v113, v114, 1.0
	v_fmac_f32_e32 v114, v115, v114
	v_div_scale_f32 v115, vcc, 1.0, v112, 1.0
	v_mul_f32_e32 v116, v115, v114
	v_fma_f32 v117, -v113, v116, v115
	v_fmac_f32_e32 v116, v117, v114
	v_fma_f32 v113, -v113, v116, v115
	v_div_fmas_f32 v113, v113, v114, v116
	v_div_fixup_f32 v112, v113, v112, 1.0
	v_pk_mul_f32 v[104:105], v[104:105], v[112:113] op_sel_hi:[1,0]
	v_pk_mul_f32 v[106:107], v[106:107], v[112:113] op_sel_hi:[1,0]
	s_nop 0
	v_pk_mul_f32 v[104:105], v[100:101], v[104:105]
	v_pk_mul_f32 v[106:107], v[102:103], v[106:107]
	v_pk_mul_f32 v[104:105], v[104:105], v[110:111]
	v_pk_mul_f32 v[106:107], v[106:107], v[108:109]
	v_bfe_u32 v108, v104, 16, 1
	v_add3_u32 v104, v104, v108, s72
	v_bfe_u32 v108, v105, 16, 1
	v_lshrrev_b32_e32 v104, 16, v104
	v_add3_u32 v105, v105, v108, s72
	s_add_u32 s38, s38, s42
	v_and_or_b32 v104, v105, s88, v104
	v_bfe_u32 v105, v106, 16, 1
	s_addc_u32 s39, s39, s43
	s_lshl_b32 s42, s52, 1
	v_add3_u32 v105, v106, v105, s72
	v_bfe_u32 v106, v107, 16, 1
	s_add_u32 s38, s38, s42
	v_lshrrev_b32_e32 v105, 16, v105
	v_add3_u32 v106, v107, v106, s72
	s_addc_u32 s39, s39, 0
	v_and_or_b32 v105, v106, s88, v105
	v_lshl_add_u64 v[106:107], v[166:167], 1, s[38:39]
	v_add_co_u32_e32 v106, vcc, 0x76fc0000, v106
	s_nop 1
	v_addc_co_u32_e32 v107, vcc, 0, v107, vcc
	global_store_dwordx2 v[106:107], v[104:105], off
.LBB0_1422:
	v_readlane_b32 s38, v253, 49
	s_cmp_ge_u32 s33, s67
	s_nop 0
	v_add_u32_e32 v104, s38, v192
	ds_read_b128 v[116:119], v104
	v_readlane_b32 s38, v253, 50
	s_waitcnt lgkmcnt(0)
	v_mov_b32_e32 v105, v118
	v_add_u32_e32 v104, s38, v192
	ds_read_b128 v[112:115], v104
	v_readlane_b32 s38, v253, 51
	v_mov_b32_e32 v106, v116
	v_mov_b32_e32 v107, v119
	v_add_u32_e32 v108, s38, v192
	ds_read_b128 v[108:111], v108
	v_mov_b32_e32 v104, v117
	v_pk_add_f32 v[104:105], v[104:105], v[106:107]
	s_waitcnt lgkmcnt(1)
	v_mov_b32_e32 v106, v112
	v_add_f32_e32 v128, v104, v105
	v_mov_b32_e32 v104, v113
	v_mov_b32_e32 v105, v114
	v_mov_b32_e32 v107, v115
	v_pk_add_f32 v[104:105], v[104:105], v[106:107]
	v_readlane_b32 s38, v253, 52
	v_add_f32_e32 v129, v104, v105
	s_waitcnt lgkmcnt(0)
	v_mov_b32_e32 v124, v109
	v_add_u32_e32 v104, s38, v192
	ds_read_b128 v[104:107], v104
	v_mov_b32_e32 v125, v110
	v_mov_b32_e32 v126, v108
	v_mov_b32_e32 v127, v111
	v_pk_add_f32 v[124:125], v[124:125], v[126:127]
	s_waitcnt lgkmcnt(0)
	v_mov_b32_e32 v126, v104
	v_add_f32_e32 v130, v124, v125
	v_mov_b32_e32 v124, v105
	v_mov_b32_e32 v125, v106
	v_mov_b32_e32 v127, v107
	v_pk_add_f32 v[124:125], v[124:125], v[126:127]
	ds_bpermute_b32 v126, v1, v129
	v_add_f32_e32 v124, v124, v125
	ds_bpermute_b32 v125, v1, v128
	ds_bpermute_b32 v127, v1, v130
	ds_bpermute_b32 v131, v1, v124
	s_waitcnt lgkmcnt(3)
	v_add_f32_e32 v126, v129, v126
	ds_bpermute_b32 v129, v3, v126
	s_waitcnt lgkmcnt(3)
	v_add_f32_e32 v125, v128, v125
	ds_bpermute_b32 v128, v3, v125
	s_waitcnt lgkmcnt(3)
	v_add_f32_e32 v127, v130, v127
	ds_bpermute_b32 v130, v3, v127
	s_waitcnt lgkmcnt(3)
	v_add_f32_e32 v124, v124, v131
	ds_bpermute_b32 v131, v3, v124
	s_waitcnt lgkmcnt(2)
	v_add_f32_e32 v125, v125, v128
	ds_bpermute_b32 v128, v120, v125
	v_add_f32_e32 v126, v126, v129
	ds_bpermute_b32 v129, v120, v126
	s_waitcnt lgkmcnt(3)
	v_add_f32_e32 v127, v127, v130
	ds_bpermute_b32 v130, v120, v127
	s_waitcnt lgkmcnt(3)
	v_add_f32_e32 v124, v124, v131
	s_waitcnt lgkmcnt(2)
	v_add_f32_e32 v125, v125, v128
	ds_bpermute_b32 v131, v120, v124
	ds_bpermute_b32 v128, v121, v125
	s_waitcnt lgkmcnt(3)
	v_add_f32_e32 v126, v126, v129
	ds_bpermute_b32 v129, v121, v126
	s_waitcnt lgkmcnt(3)
	v_add_f32_e32 v127, v127, v130
	ds_bpermute_b32 v130, v121, v127
	s_waitcnt lgkmcnt(3)
	v_add_f32_e32 v124, v124, v131
	s_waitcnt lgkmcnt(2)
	v_add_f32_e32 v125, v125, v128
	ds_bpermute_b32 v131, v121, v124
	ds_bpermute_b32 v128, v122, v125
	s_waitcnt lgkmcnt(3)
	v_add_f32_e32 v126, v126, v129
	ds_bpermute_b32 v129, v122, v126
	s_waitcnt lgkmcnt(3)
	v_add_f32_e32 v127, v127, v130
	ds_bpermute_b32 v130, v122, v127
	s_waitcnt lgkmcnt(3)
	v_add_f32_e32 v124, v124, v131
	s_waitcnt lgkmcnt(2)
	v_add_f32_e32 v125, v125, v128
	ds_bpermute_b32 v131, v122, v124
	ds_bpermute_b32 v128, v123, v125
	s_waitcnt lgkmcnt(3)
	v_add_f32_e32 v126, v126, v129
	ds_bpermute_b32 v129, v123, v126
	s_waitcnt lgkmcnt(3)
	v_add_f32_e32 v127, v127, v130
	ds_bpermute_b32 v130, v123, v127
	s_waitcnt lgkmcnt(3)
	v_add_f32_e32 v124, v124, v131
	s_waitcnt lgkmcnt(2)
; #define GAS __attribute__((address_space(1)))
; __device__ __forceinline__ unsigned pk2(float lo, float hi) { return f2bf(lo) | (f2bf(hi) << 16); }
; #define WSB(F, off) ((bf16*)(wsq((F).ws) + (off)))
; __device__ __forceinline__ void ret_unit(const Frame& F, int layer, int uid) {
;     ...
;             for (int o = 1; o < 64; o <<= 1)
; #pragma unroll
;                 for (int tt = 0; tt < 4; ++tt) s1[tt] += __shfl_xor(s1[tt], o);
; #pragma unroll
;             for (int tt = 0; tt < 4; ++tt) { x[tt] = x[tt] - s1[tt] * (1.f / 256.f); s2[tt] = (x[tt][0] * x[tt][0] + x[tt][1] * x[tt][1]) + (x[tt][2] * x[tt][2] + x[tt][3] * x[tt][3]); }
; #pragma unroll
;             for (int o = 1; o < 64; o <<= 1)
; #pragma unroll
;                 for (int tt = 0; tt < 4; ++tt) s2[tt] += __shfl_xor(s2[tt], o);
; #pragma unroll
;             for (int tt = 0; tt < 4; ++tt) { const int t = w * 8 + hb2 * 4 + tt; const float rstd = 1.f / sqrtf(s2[tt] * (1.f / 256.f) + LN_EPS);
;                 const f32x4 y = x[tt] * rstd * gn * (f32x4){bflo(gr[tt].x), bfhi(gr[tt].x), bflo(gr[tt].y), bfhi(gr[tt].y)};
;                 if (t < valid) *(GAS v2u*)(WSB(F, WS_BR) + (size_t)(rowbase + t) * D + h * 256 + lane * 4) = (v2u){pk2(y[0], y[1]), pk2(y[2], y[3])}; }
	v_add_f32_e32 v125, v125, v128
	ds_bpermute_b32 v131, v123, v124
	v_fmamk_f32 v119, v125, 0xbb800000, v119
	v_fmamk_f32 v117, v125, 0xbb800000, v117
	s_waitcnt lgkmcnt(2)
	v_add_f32_e32 v126, v126, v129
	v_fmamk_f32 v118, v125, 0xbb800000, v118
	v_fmac_f32_e32 v116, 0xbb800000, v125
	v_mul_f32_e32 v125, v117, v117
	v_mul_f32_e32 v128, v119, v119
	v_fmac_f32_e32 v125, v116, v116
	v_fmac_f32_e32 v128, v118, v118
	v_fmamk_f32 v115, v126, 0xbb800000, v115
	v_fmamk_f32 v113, v126, 0xbb800000, v113
	s_waitcnt lgkmcnt(1)
	v_add_f32_e32 v127, v127, v130
	v_add_f32_e32 v125, v125, v128
	v_fmamk_f32 v114, v126, 0xbb800000, v114
	v_fmac_f32_e32 v112, 0xbb800000, v126
	v_mul_f32_e32 v126, v113, v113
	v_mul_f32_e32 v128, v115, v115
	v_fmac_f32_e32 v126, v112, v112
	v_fmac_f32_e32 v128, v114, v114
	v_fmamk_f32 v111, v127, 0xbb800000, v111
	v_fmamk_f32 v109, v127, 0xbb800000, v109
	s_waitcnt lgkmcnt(0)
	v_add_f32_e32 v124, v124, v131
	v_add_f32_e32 v126, v126, v128
	v_fmamk_f32 v110, v127, 0xbb800000, v110
	v_fmac_f32_e32 v108, 0xbb800000, v127
	v_mul_f32_e32 v127, v109, v109
	v_mul_f32_e32 v128, v111, v111
	v_fmac_f32_e32 v127, v108, v108
	v_fmac_f32_e32 v128, v110, v110
	v_fmamk_f32 v107, v124, 0xbb800000, v107
	v_fmamk_f32 v105, v124, 0xbb800000, v105
	v_add_f32_e32 v127, v127, v128
	v_fmamk_f32 v106, v124, 0xbb800000, v106
	v_fmac_f32_e32 v104, 0xbb800000, v124
	v_mul_f32_e32 v124, v105, v105
	v_mul_f32_e32 v128, v107, v107
	v_fmac_f32_e32 v124, v104, v104
	v_fmac_f32_e32 v128, v106, v106
	v_add_f32_e32 v124, v124, v128
	ds_bpermute_b32 v128, v1, v125
	ds_bpermute_b32 v129, v1, v126
	ds_bpermute_b32 v130, v1, v127
	ds_bpermute_b32 v1, v1, v124
	s_waitcnt lgkmcnt(3)
	v_add_f32_e32 v125, v125, v128
	s_waitcnt lgkmcnt(2)
	v_add_f32_e32 v126, v126, v129
	s_waitcnt lgkmcnt(1)
	v_add_f32_e32 v127, v127, v130
	s_waitcnt lgkmcnt(0)
	v_add_f32_e32 v1, v124, v1
	ds_bpermute_b32 v124, v3, v125
	ds_bpermute_b32 v128, v3, v126
	ds_bpermute_b32 v129, v3, v127
	ds_bpermute_b32 v3, v3, v1
	s_waitcnt lgkmcnt(3)
	v_add_f32_e32 v124, v125, v124
	s_waitcnt lgkmcnt(2)
	v_add_f32_e32 v125, v126, v128
	s_waitcnt lgkmcnt(1)
	v_add_f32_e32 v126, v127, v129
	s_waitcnt lgkmcnt(0)
	v_add_f32_e32 v1, v1, v3
	ds_bpermute_b32 v3, v120, v124
	ds_bpermute_b32 v127, v120, v125
	ds_bpermute_b32 v128, v120, v126
	ds_bpermute_b32 v120, v120, v1
	s_waitcnt lgkmcnt(3)
	v_add_f32_e32 v3, v124, v3
	s_waitcnt lgkmcnt(2)
	v_add_f32_e32 v124, v125, v127
	s_waitcnt lgkmcnt(1)
	v_add_f32_e32 v125, v126, v128
	s_waitcnt lgkmcnt(0)
	v_add_f32_e32 v1, v1, v120
	ds_bpermute_b32 v120, v121, v3
	ds_bpermute_b32 v126, v121, v124
	ds_bpermute_b32 v127, v121, v125
	ds_bpermute_b32 v121, v121, v1
	s_waitcnt lgkmcnt(3)
	v_add_f32_e32 v3, v3, v120
	s_waitcnt lgkmcnt(2)
	v_add_f32_e32 v120, v124, v126
	s_waitcnt lgkmcnt(1)
	v_add_f32_e32 v124, v125, v127
	s_waitcnt lgkmcnt(0)
	v_add_f32_e32 v1, v1, v121
	ds_bpermute_b32 v121, v122, v3
	ds_bpermute_b32 v126, v122, v120
	ds_bpermute_b32 v127, v122, v124
	ds_bpermute_b32 v128, v122, v1
	s_waitcnt lgkmcnt(3)
	v_add_f32_e32 v125, v3, v121
	s_waitcnt lgkmcnt(2)
	v_add_f32_e32 v122, v120, v126
	s_waitcnt lgkmcnt(1)
	v_add_f32_e32 v120, v124, v127
	s_waitcnt lgkmcnt(0)
	v_add_f32_e32 v1, v1, v128
	ds_bpermute_b32 v126, v123, v125
	ds_bpermute_b32 v124, v123, v122
	ds_bpermute_b32 v121, v123, v120
	ds_bpermute_b32 v3, v123, v1
	s_cbranch_scc1 .LBB0_1428
	s_waitcnt lgkmcnt(3)
	v_add_f32_e32 v123, v125, v126
	v_fmamk_f32 v123, v123, 0x3b800000, v235
	v_mul_f32_e32 v125, 0x4f800000, v123
	v_cmp_gt_f32_e32 vcc, s89, v123
	s_nop 0
	v_and_b32_e32 v129, 0xffff0000, v174
	s_add_i32 s42, s78, s33
	v_cndmask_b32_e32 v123, v123, v125, vcc
	v_sqrt_f32_e32 v125, v123
	s_ashr_i32 s43, s42, 31
	v_and_b32_e32 v127, 0xffff0000, v175
	s_lshl_b64 s[42:43], s[42:43], 11
	v_add_u32_e32 v126, -1, v125
	v_fma_f32 v128, -v126, v125, v123
	v_cmp_ge_f32_e64 s[38:39], 0, v128
	v_add_u32_e32 v128, 1, v125
	s_nop 0
	v_cndmask_b32_e64 v126, v125, v126, s[38:39]
	v_fma_f32 v125, -v128, v125, v123
	v_cmp_lt_f32_e64 s[38:39], 0, v125
	s_nop 1
	v_cndmask_b32_e64 v125, v126, v128, s[38:39]
	v_mul_f32_e32 v126, 0x37800000, v125
	v_cndmask_b32_e32 v125, v125, v126, vcc
	v_cmp_class_f32_e32 vcc, v123, v236
	v_lshlrev_b32_e32 v128, 16, v174
	v_lshlrev_b32_e32 v126, 16, v175
	v_cndmask_b32_e32 v123, v125, v123, vcc
	v_div_scale_f32 v125, s[38:39], v123, v123, 1.0
	v_rcp_f32_e32 v130, v125
	s_mov_b64 s[38:39], s[46:47]
	s_add_u32 s38, s38, s42
	v_fma_f32 v131, -v125, v130, 1.0
	v_fmac_f32_e32 v130, v131, v130
	v_div_scale_f32 v131, vcc, 1.0, v123, 1.0
	v_mul_f32_e32 v132, v131, v130
	v_fma_f32 v133, -v125, v132, v131
	v_fmac_f32_e32 v132, v133, v130
	v_fma_f32 v125, -v125, v132, v131
	v_div_fmas_f32 v125, v125, v130, v132
	v_div_fixup_f32 v130, v125, v123, 1.0
	v_pk_mul_f32 v[116:117], v[116:117], v[130:131] op_sel_hi:[1,0]
	v_pk_mul_f32 v[118:119], v[118:119], v[130:131] op_sel_hi:[1,0]
	s_nop 0
	v_pk_mul_f32 v[116:117], v[100:101], v[116:117]
	v_pk_mul_f32 v[118:119], v[102:103], v[118:119]
	v_pk_mul_f32 v[116:117], v[116:117], v[128:129]
	v_pk_mul_f32 v[118:119], v[118:119], v[126:127]
	v_bfe_u32 v123, v116, 16, 1
	v_add3_u32 v116, v116, v123, s72
	v_bfe_u32 v123, v117, 16, 1
	v_lshrrev_b32_e32 v116, 16, v116
	v_add3_u32 v117, v117, v123, s72
	v_and_or_b32 v116, v117, s88, v116
	v_bfe_u32 v117, v118, 16, 1
	s_addc_u32 s39, s39, s43
	s_lshl_b32 s42, s52, 1
	v_add3_u32 v117, v118, v117, s72
	v_bfe_u32 v118, v119, 16, 1
	s_add_u32 s38, s38, s42
	v_lshrrev_b32_e32 v117, 16, v117
	v_add3_u32 v118, v119, v118, s72
	s_addc_u32 s39, s39, 0
	v_and_or_b32 v117, v118, s88, v117
	v_lshl_add_u64 v[118:119], v[166:167], 1, s[38:39]
	v_add_co_u32_e32 v118, vcc, 0x76fc0000, v118
	s_nop 1
	v_addc_co_u32_e32 v119, vcc, 0, v119, vcc
	global_store_dwordx2 v[118:119], v[116:117], off
	s_cmp_ge_u32 s84, s67
	s_cbranch_scc0 .LBB0_1429

; #define GAS __attribute__((address_space(1)))
; __device__ __forceinline__ unsigned pk2(float lo, float hi) { return f2bf(lo) | (f2bf(hi) << 16); }
; #define WSB(F, off) ((bf16*)(wsq((F).ws) + (off)))
; __device__ __forceinline__ void ret_unit(const Frame& F, int layer, int uid) {
;     ...
;             for (int tt = 0; tt < 4; ++tt) { const int t = w * 8 + hb2 * 4 + tt; const float rstd = 1.f / sqrtf(s2[tt] * (1.f / 256.f) + LN_EPS);
;                 const f32x4 y = x[tt] * rstd * gn * (f32x4){bflo(gr[tt].x), bfhi(gr[tt].x), bflo(gr[tt].y), bfhi(gr[tt].y)};
;                 if (t < valid) *(GAS v2u*)(WSB(F, WS_BR) + (size_t)(rowbase + t) * D + h * 256 + lane * 4) = (v2u){pk2(y[0], y[1]), pk2(y[2], y[3])}; }
.LBB0_1425:
	s_waitcnt lgkmcnt(1)
	v_add_f32_e32 v112, v120, v121
	v_fmamk_f32 v112, v112, 0x3b800000, v235
	v_mul_f32_e32 v113, 0x4f800000, v112
	v_cmp_gt_f32_e32 vcc, s89, v112
	s_add_i32 s42, s78, s77
	s_ashr_i32 s43, s42, 31
	v_cndmask_b32_e32 v112, v112, v113, vcc
	v_sqrt_f32_e32 v114, v112
	s_nop 0
	v_and_b32_e32 v113, 0xffff0000, v171
	s_lshl_b64 s[42:43], s[42:43], 11
	v_add_u32_e32 v115, -1, v114
	v_fma_f32 v116, -v115, v114, v112
	v_cmp_ge_f32_e64 s[38:39], 0, v116
	v_add_u32_e32 v116, 1, v114
	s_nop 0
	v_cndmask_b32_e64 v115, v114, v115, s[38:39]
	v_fma_f32 v114, -v116, v114, v112
	v_cmp_lt_f32_e64 s[38:39], 0, v114
	s_nop 1
	v_cndmask_b32_e64 v114, v115, v116, s[38:39]
	v_mul_f32_e32 v115, 0x37800000, v114
	v_cndmask_b32_e32 v114, v114, v115, vcc
	v_cmp_class_f32_e32 vcc, v112, v236
	v_and_b32_e32 v115, 0xffff0000, v170
	s_nop 0
	v_cndmask_b32_e32 v116, v114, v112, vcc
	v_div_scale_f32 v117, s[38:39], v116, v116, 1.0
	v_rcp_f32_e32 v118, v117
	v_lshlrev_b32_e32 v114, 16, v170
	v_lshlrev_b32_e32 v112, 16, v171
	s_mov_b64 s[38:39], s[46:47]
	v_fma_f32 v119, -v117, v118, 1.0
	v_fmac_f32_e32 v118, v119, v118
	v_div_scale_f32 v119, vcc, 1.0, v116, 1.0
	v_mul_f32_e32 v120, v119, v118
	v_fma_f32 v121, -v117, v120, v119
	v_fmac_f32_e32 v120, v121, v118
	v_fma_f32 v117, -v117, v120, v119
	v_div_fmas_f32 v117, v117, v118, v120
	v_div_fixup_f32 v116, v117, v116, 1.0
	v_pk_mul_f32 v[108:109], v[108:109], v[116:117] op_sel_hi:[1,0]
	v_pk_mul_f32 v[110:111], v[110:111], v[116:117] op_sel_hi:[1,0]
	s_nop 0
	v_pk_mul_f32 v[108:109], v[100:101], v[108:109]
	v_pk_mul_f32 v[110:111], v[102:103], v[110:111]
	v_pk_mul_f32 v[108:109], v[108:109], v[114:115]
	v_pk_mul_f32 v[110:111], v[110:111], v[112:113]
	v_bfe_u32 v112, v108, 16, 1
	v_add3_u32 v108, v108, v112, s72
	v_bfe_u32 v112, v109, 16, 1
	v_lshrrev_b32_e32 v108, 16, v108
	v_add3_u32 v109, v109, v112, s72
	s_add_u32 s38, s38, s42
	v_and_or_b32 v108, v109, s88, v108
	v_bfe_u32 v109, v110, 16, 1
	s_addc_u32 s39, s39, s43
	s_lshl_b32 s42, s52, 1
	v_add3_u32 v109, v110, v109, s72
	v_bfe_u32 v110, v111, 16, 1
	s_add_u32 s38, s38, s42
	v_lshrrev_b32_e32 v109, 16, v109
	v_add3_u32 v110, v111, v110, s72
	s_addc_u32 s39, s39, 0
	v_and_or_b32 v109, v110, s88, v109
	v_lshl_add_u64 v[110:111], v[166:167], 1, s[38:39]
	v_add_co_u32_e32 v110, vcc, 0x76fc0000, v110
	s_nop 1
	v_addc_co_u32_e32 v111, vcc, 0, v111, vcc
	global_store_dwordx2 v[110:111], v[108:109], off
	s_cmp_ge_u32 s71, s67
	s_cbranch_scc1 .LBB0_1380
	s_branch .LBB0_1431

; #define GAS __attribute__((address_space(1)))
; __device__ __forceinline__ unsigned pk2(float lo, float hi) { return f2bf(lo) | (f2bf(hi) << 16); }
; #define WSB(F, off) ((bf16*)(wsq((F).ws) + (off)))
; __device__ __forceinline__ void ret_unit(const Frame& F, int layer, int uid) {
;     ...
;             for (int tt = 0; tt < 4; ++tt) { const int t = w * 8 + hb2 * 4 + tt; const float rstd = 1.f / sqrtf(s2[tt] * (1.f / 256.f) + LN_EPS);
;                 const f32x4 y = x[tt] * rstd * gn * (f32x4){bflo(gr[tt].x), bfhi(gr[tt].x), bflo(gr[tt].y), bfhi(gr[tt].y)};
;                 if (t < valid) *(GAS v2u*)(WSB(F, WS_BR) + (size_t)(rowbase + t) * D + h * 256 + lane * 4) = (v2u){pk2(y[0], y[1]), pk2(y[2], y[3])}; }
.LBB0_1429:
	s_waitcnt lgkmcnt(2)
	v_add_f32_e32 v116, v122, v124
	v_fmamk_f32 v116, v116, 0x3b800000, v235
	v_mul_f32_e32 v117, 0x4f800000, v116
	v_cmp_gt_f32_e32 vcc, s89, v116
	s_add_i32 s42, s78, s84
	s_ashr_i32 s43, s42, 31
	v_cndmask_b32_e32 v116, v116, v117, vcc
	v_sqrt_f32_e32 v118, v116
	s_nop 0
	v_and_b32_e32 v117, 0xffff0000, v173
	s_lshl_b64 s[42:43], s[42:43], 11
	v_add_u32_e32 v119, -1, v118
	v_fma_f32 v122, -v119, v118, v116
	v_cmp_ge_f32_e64 s[38:39], 0, v122
	v_add_u32_e32 v122, 1, v118
	s_nop 0
	v_cndmask_b32_e64 v119, v118, v119, s[38:39]
	v_fma_f32 v118, -v122, v118, v116
	v_cmp_lt_f32_e64 s[38:39], 0, v118
	s_nop 1
	v_cndmask_b32_e64 v118, v119, v122, s[38:39]
	v_mul_f32_e32 v119, 0x37800000, v118
	v_cndmask_b32_e32 v118, v118, v119, vcc
	v_cmp_class_f32_e32 vcc, v116, v236
	v_and_b32_e32 v119, 0xffff0000, v172
	s_nop 0
	v_cndmask_b32_e32 v122, v118, v116, vcc
	v_div_scale_f32 v123, s[38:39], v122, v122, 1.0
	v_rcp_f32_e32 v124, v123
	v_lshlrev_b32_e32 v118, 16, v172
	v_lshlrev_b32_e32 v116, 16, v173
	s_mov_b64 s[38:39], s[46:47]
	v_fma_f32 v125, -v123, v124, 1.0
	v_fmac_f32_e32 v124, v125, v124
	v_div_scale_f32 v125, vcc, 1.0, v122, 1.0
	v_mul_f32_e32 v126, v125, v124
	v_fma_f32 v127, -v123, v126, v125
	v_fmac_f32_e32 v126, v127, v124
	v_fma_f32 v123, -v123, v126, v125
	v_div_fmas_f32 v123, v123, v124, v126
	v_div_fixup_f32 v122, v123, v122, 1.0
	v_pk_mul_f32 v[112:113], v[112:113], v[122:123] op_sel_hi:[1,0]
	v_pk_mul_f32 v[114:115], v[114:115], v[122:123] op_sel_hi:[1,0]
	s_nop 0
	v_pk_mul_f32 v[112:113], v[100:101], v[112:113]
	v_pk_mul_f32 v[114:115], v[102:103], v[114:115]
	v_pk_mul_f32 v[112:113], v[112:113], v[118:119]
	v_pk_mul_f32 v[114:115], v[114:115], v[116:117]
	v_bfe_u32 v116, v112, 16, 1
	v_add3_u32 v112, v112, v116, s72
	v_bfe_u32 v116, v113, 16, 1
	v_lshrrev_b32_e32 v112, 16, v112
	v_add3_u32 v113, v113, v116, s72
	s_add_u32 s38, s38, s42
	v_and_or_b32 v112, v113, s88, v112
	v_bfe_u32 v113, v114, 16, 1
	s_addc_u32 s39, s39, s43
	s_lshl_b32 s42, s52, 1
	v_add3_u32 v113, v114, v113, s72
	v_bfe_u32 v114, v115, 16, 1
	s_add_u32 s38, s38, s42
	v_lshrrev_b32_e32 v113, 16, v113
	v_add3_u32 v114, v115, v114, s72
	s_addc_u32 s39, s39, 0
	v_and_or_b32 v113, v114, s88, v113
	v_lshl_add_u64 v[114:115], v[166:167], 1, s[38:39]
	v_add_co_u32_e32 v114, vcc, 0x76fc0000, v114
	s_nop 1
	v_addc_co_u32_e32 v115, vcc, 0, v115, vcc
	global_store_dwordx2 v[114:115], v[112:113], off
	s_cmp_ge_u32 s77, s67
	s_cbranch_scc0 .LBB0_1425

; #define GAS __attribute__((address_space(1)))
; __device__ __forceinline__ unsigned pk2(float lo, float hi) { return f2bf(lo) | (f2bf(hi) << 16); }
; #define WSB(F, off) ((bf16*)(wsq((F).ws) + (off)))
; __device__ __forceinline__ void ret_unit(const Frame& F, int layer, int uid) {
;     ...
;             for (int tt = 0; tt < 4; ++tt) { const int t = w * 8 + hb2 * 4 + tt; const float rstd = 1.f / sqrtf(s2[tt] * (1.f / 256.f) + LN_EPS);
;                 const f32x4 y = x[tt] * rstd * gn * (f32x4){bflo(gr[tt].x), bfhi(gr[tt].x), bflo(gr[tt].y), bfhi(gr[tt].y)};
;                 if (t < valid) *(GAS v2u*)(WSB(F, WS_BR) + (size_t)(rowbase + t) * D + h * 256 + lane * 4) = (v2u){pk2(y[0], y[1]), pk2(y[2], y[3])}; }
.LBB0_1431:
	s_waitcnt lgkmcnt(0)
	v_add_f32_e32 v1, v1, v3
	v_fmamk_f32 v1, v1, 0x3b800000, v235
	v_mul_f32_e32 v3, 0x4f800000, v1
	v_cmp_gt_f32_e32 vcc, s89, v1
	s_add_i32 s42, s78, s71
	s_nop 0
	v_and_b32_e32 v111, 0xffff0000, v168
	v_cndmask_b32_e32 v1, v1, v3, vcc
	v_sqrt_f32_e32 v3, v1
	s_ashr_i32 s43, s42, 31
	s_lshl_b64 s[42:43], s[42:43], 11
	v_and_b32_e32 v109, 0xffff0000, v169
	v_add_u32_e32 v108, -1, v3
	v_fma_f32 v110, -v108, v3, v1
	v_cmp_ge_f32_e64 s[38:39], 0, v110
	v_add_u32_e32 v110, 1, v3
	s_nop 0
	v_cndmask_b32_e64 v108, v3, v108, s[38:39]
	v_fma_f32 v3, -v110, v3, v1
	v_cmp_lt_f32_e64 s[38:39], 0, v3
	s_nop 1
	v_cndmask_b32_e64 v3, v108, v110, s[38:39]
	v_mul_f32_e32 v108, 0x37800000, v3
	v_cndmask_b32_e32 v3, v3, v108, vcc
	v_cmp_class_f32_e32 vcc, v1, v236
	v_lshlrev_b32_e32 v110, 16, v168
	v_lshlrev_b32_e32 v108, 16, v169
	v_cndmask_b32_e32 v1, v3, v1, vcc
	v_div_scale_f32 v3, s[38:39], v1, v1, 1.0
	v_rcp_f32_e32 v112, v3
	s_mov_b64 s[38:39], s[46:47]
	s_add_u32 s38, s38, s42
	v_fma_f32 v113, -v3, v112, 1.0
	v_fmac_f32_e32 v112, v113, v112
	v_div_scale_f32 v113, vcc, 1.0, v1, 1.0
	v_mul_f32_e32 v114, v113, v112
	v_fma_f32 v115, -v3, v114, v113
	v_fmac_f32_e32 v114, v115, v112
	v_fma_f32 v3, -v3, v114, v113
	v_div_fmas_f32 v3, v3, v112, v114
	v_div_fixup_f32 v112, v3, v1, 1.0
	v_pk_mul_f32 v[104:105], v[104:105], v[112:113] op_sel_hi:[1,0]
	v_pk_mul_f32 v[106:107], v[106:107], v[112:113] op_sel_hi:[1,0]
	s_nop 0
	v_pk_mul_f32 v[100:101], v[100:101], v[104:105]
	v_pk_mul_f32 v[102:103], v[102:103], v[106:107]
	v_pk_mul_f32 v[100:101], v[100:101], v[110:111]
	s_addc_u32 s39, s39, s43
	v_bfe_u32 v1, v100, 16, 1
	v_add3_u32 v1, v100, v1, s72
	v_bfe_u32 v3, v101, 16, 1
	s_lshl_b32 s42, s52, 1
	v_pk_mul_f32 v[102:103], v[102:103], v[108:109]
	v_lshrrev_b32_e32 v1, 16, v1
	v_add3_u32 v3, v101, v3, s72
	s_add_u32 s38, s38, s42
	v_and_or_b32 v100, v3, s88, v1
	v_bfe_u32 v1, v102, 16, 1
	v_bfe_u32 v3, v103, 16, 1
	s_addc_u32 s39, s39, 0
	v_add3_u32 v1, v102, v1, s72
	v_add3_u32 v3, v103, v3, s72
	v_lshl_add_u64 v[102:103], v[166:167], 1, s[38:39]
	v_lshrrev_b32_e32 v1, 16, v1
	v_add_co_u32_e32 v102, vcc, 0x76fc0000, v102
	v_and_or_b32 v101, v3, s88, v1
	s_nop 0
	v_addc_co_u32_e32 v103, vcc, 0, v103, vcc
	global_store_dwordx2 v[102:103], v[100:101], off
	s_branch .LBB0_1380

; __global__ void __launch_bounds__(512, 2) mega_fwd(Args args) {
	.amdhsa_kernel _Z8mega_fwd4Args
		.amdhsa_group_segment_fixed_size 0
		.amdhsa_private_segment_fixed_size 0
		.amdhsa_kernarg_size 424
		.amdhsa_user_sgpr_count 2
		.amdhsa_user_sgpr_dispatch_ptr 0
		.amdhsa_user_sgpr_queue_ptr 0
		.amdhsa_user_sgpr_kernarg_segment_ptr 1
		.amdhsa_user_sgpr_dispatch_id 0
		.amdhsa_user_sgpr_kernarg_preload_length 0
		.amdhsa_user_sgpr_kernarg_preload_offset 0
		.amdhsa_user_sgpr_private_segment_size 0
		.amdhsa_uses_dynamic_stack 0
		.amdhsa_enable_private_segment 0
		.amdhsa_system_sgpr_workgroup_id_x 1
		.amdhsa_system_sgpr_workgroup_id_y 0
		.amdhsa_system_sgpr_workgroup_id_z 0
		.amdhsa_system_sgpr_workgroup_info 0
		.amdhsa_system_vgpr_workitem_id 0
		.amdhsa_next_free_vgpr 255
		.amdhsa_next_free_sgpr 102
		.amdhsa_accum_offset 256
		.amdhsa_reserve_vcc 1
		.amdhsa_float_round_mode_32 0
		.amdhsa_float_round_mode_16_64 0
		.amdhsa_float_denorm_mode_32 3
		.amdhsa_float_denorm_mode_16_64 3
		.amdhsa_dx10_clamp 1
		.amdhsa_ieee_mode 1
		.amdhsa_fp16_overflow 0
		.amdhsa_tg_split 0
		.amdhsa_exception_fp_ieee_invalid_op 0
		.amdhsa_exception_fp_denorm_src 0
		.amdhsa_exception_fp_ieee_div_zero 0
		.amdhsa_exception_fp_ieee_overflow 0
		.amdhsa_exception_fp_ieee_underflow 0
		.amdhsa_exception_fp_ieee_inexact 0
		.amdhsa_exception_int_div_zero 0
	.end_amdhsa_kernel

; __global__ void __launch_bounds__(512, 2) mega_fwd(Args args) {
amdhsa.kernels:
  - .agpr_count:     0
    .args:
      - .offset:         0
        .size:           168
        .value_kind:     by_value
      - .offset:         168
        .size:           4
        .value_kind:     hidden_block_count_x
      - .offset:         172
        .size:           4
        .value_kind:     hidden_block_count_y
      - .offset:         176
        .size:           4
        .value_kind:     hidden_block_count_z
      - .offset:         180
        .size:           2
        .value_kind:     hidden_group_size_x
      - .offset:         182
        .size:           2
        .value_kind:     hidden_group_size_y
      - .offset:         184
        .size:           2
        .value_kind:     hidden_group_size_z
      - .offset:         186
        .size:           2
        .value_kind:     hidden_remainder_x
      - .offset:         188
        .size:           2
        .value_kind:     hidden_remainder_y
      - .offset:         190
        .size:           2
        .value_kind:     hidden_remainder_z
      - .offset:         208
        .size:           8
        .value_kind:     hidden_global_offset_x
      - .offset:         216
        .size:           8
        .value_kind:     hidden_global_offset_y
      - .offset:         224
        .size:           8
        .value_kind:     hidden_global_offset_z
      - .offset:         232
        .size:           2
        .value_kind:     hidden_grid_dims
      - .offset:         288
        .size:           4
        .value_kind:     hidden_dynamic_lds_size
    .group_segment_fixed_size: 0
    .kernarg_segment_align: 8
    .kernarg_segment_size: 424
    .language:       OpenCL C
    .language_version:
      - 2
      - 0
    .max_flat_workgroup_size: 512
    .name:           _Z8mega_fwd4Args
    .private_segment_fixed_size: 0
    .sgpr_count:     108
    .sgpr_spill_count: 160
    .symbol:         _Z8mega_fwd4Args.kd
    .uniform_work_group_size: 1
    .uses_dynamic_stack: false
    .vgpr_count:     255
    .vgpr_spill_count: 0
    .wavefront_size: 64
